# P3 tile prologues: SSQ->rs scale loads overlapped with the tile's 16 staging loads (finish under vmcnt(16)) instead of a full round trip before them
# baseline (speedup 1.0000x reference)
; template <bool SWAP, class Epi>
; DI void gemm_tile(const u16* __restrict__ A, int lda, const u16* __restrict__ Bt, int ldb, int K, int m0, int n0, char* smem, Epi&& epi) {
;     ...
;   const int srow = tid >> 3, skc = tid & 7;
;   const u16* ag = A + (size_t)(m0 + srow) * lda + skc * 8;
;   const u16* bg = Bt + (size_t)(n0 + srow) * ldb + skc * 8;
;   u16* asw = As + srow * 72 + skc * 8;
;   u16* bsw = Bs + srow * 72 + skc * 8;
;   u32x4 ra0[4], rb0[4], ra1[4], rb1[4];
; #pragma unroll
;   for (int i = 0; i < 4; ++i) { ra0[i] = *(const u32x4*)(ag + (size_t)i * 32 * lda); rb0[i] = *(const u32x4*)(bg + (size_t)i * 32 * ldb); }
; #pragma unroll
;   for (int i = 0; i < 4; ++i) { ra1[i] = *(const u32x4*)(ag + (size_t)i * 32 * lda + 64); rb1[i] = *(const u32x4*)(bg + (size_t)i * 32 * ldb + 64); }
;   __syncthreads();
; #pragma unroll
;   for (int i = 0; i < 4; ++i) { *(u32x4*)(asw + 32 * i * 72) = ra0[i]; *(u32x4*)(bsw + 32 * i * 72) = rb0[i]; }
;   __syncthreads();
;   const int KT = K >> 6;
;   const u16* Asb = As + (wm * 64 + r) * 72 + hi * 8;
;   const u16* Bsb = Bs + (wn * 64 + r) * 72 + hi * 8;
;   auto compute = [&](int buf) __attribute__((always_inline)) {
;     bf16x8 af[2][2], bfr[2][2];
;     af[0][0] = *(const bf16x8*)(Asb + buf * 128 * 72);
;     af[0][1] = *(const bf16x8*)(Asb + buf * 128 * 72 + 32 * 72);
;     bfr[0][0] = *(const bf16x8*)(Bsb + buf * 128 * 72);
;     bfr[0][1] = *(const bf16x8*)(Bsb + buf * 128 * 72 + 32 * 72);
; #pragma unroll
;     for (int ks = 0; ks < 4; ++ks) {
;       const int c = ks & 1, n = c ^ 1;
;       if (ks < 3) {
;         af[n][0] = *(const bf16x8*)(Asb + buf * 128 * 72 + (ks + 1) * 16);
;         af[n][1] = *(const bf16x8*)(Asb + buf * 128 * 72 + 32 * 72 + (ks + 1) * 16);
;         bfr[n][0] = *(const bf16x8*)(Bsb + buf * 128 * 72 + (ks + 1) * 16);
;         bfr[n][1] = *(const bf16x8*)(Bsb + buf * 128 * 72 + 32 * 72 + (ks + 1) * 16);
;       }
; DI void phase3(const Params& p, char* smem) {
;     ...
;       const int j2 = it - NQ, tn = j2 / 64, tm = j2 % 64;
;       __syncthreads();
;       if (threadIdx.x < 128) { const float4* sp = (const float4*)(SSQ + (size_t)(tm * 128 + threadIdx.x) * 16 + 8); const float4 a = sp[0], b = sp[1]; rs[threadIdx.x] = rsqrtf((((a.x + a.y) + (a.z + a.w)) + ((b.x + b.y) + (b.z + b.w))) * (1.f / 512.f) + EPS); }
;       const int head = tn >> 1;
;       if ((tn & 1) == 0) {
.LBB0_508:
	s_cmpk_gt_i32 s13, 0x2ff
	s_mov_b64 s[50:51], -1
	s_cbranch_scc0 .LBB0_516
	s_and_b32 s92, s13, 63
	s_barrier
	s_and_saveexec_b64 s[50:51], s[2:3]
	s_cbranch_execz .LBB0_511
	v_lshl_or_b32 v242, s92, 13, v1
	global_load_dwordx4 v[238:241], v242, s[14:15] offset:32
	s_nop 0
	global_load_dwordx4 v[242:245], v242, s[14:15] offset:48
.LBB0_511:
	s_or_b64 exec, exec, s[50:51]
	s_lshl_b32 s92, s92, 7
	s_and_b32 s51, s64, 0x7fff0000
	v_or_b32_e32 v2, s92, v120
	v_mul_u32_u24_e32 v66, 0x2080, v2
	v_or_b32_e32 v2, s51, v134
	s_add_i32 s16, s13, 0xfffffd00
	v_lshl_add_u64 v[80:81], v[68:69], 0, v[66:67]
	v_lshlrev_b32_e32 v66, 1, v2
	s_lshr_b32 s16, s16, 7
	s_and_b32 s50, s13, 64
	v_lshl_add_u64 v[82:83], v[74:75], 0, v[66:67]
	s_cmp_lg_u32 s50, 0
	v_lshl_add_u64 v[90:91], v[80:81], 0, s[18:19]
	v_lshl_add_u64 v[88:89], v[80:81], 0, s[20:21]
	v_lshl_add_u64 v[86:87], v[80:81], 0, s[22:23]
	v_lshl_add_u64 v[84:85], v[80:81], 0, s[24:25]
	v_lshl_add_u64 v[106:107], v[82:83], 0, s[26:27]
	v_lshl_add_u64 v[104:105], v[82:83], 0, s[28:29]
	v_lshl_add_u64 v[102:103], v[82:83], 0, s[30:31]
	v_lshl_add_u64 v[92:93], v[82:83], 0, s[34:35]
	v_lshl_add_u64 v[94:95], v[80:81], 0, s[36:37]
	v_lshl_add_u64 v[96:97], v[82:83], 0, s[42:43]
	v_lshl_add_u64 v[98:99], v[80:81], 0, s[44:45]
	v_lshl_add_u64 v[100:101], v[82:83], 0, s[46:47]
	s_mov_b64 s[50:51], -1
	s_cbranch_scc0 .LBB0_513
	global_load_dwordx4 v[2:5], v[80:81], off
	global_load_dwordx4 v[6:9], v[82:83], off
	global_load_dwordx4 v[10:13], v[90:91], off
	global_load_dwordx4 v[14:17], v[106:107], off
	global_load_dwordx4 v[18:21], v[88:89], off
	global_load_dwordx4 v[22:25], v[104:105], off
	global_load_dwordx4 v[26:29], v[86:87], off
	global_load_dwordx4 v[30:33], v[102:103], off
	global_load_dwordx4 v[140:143], v[80:81], off offset:128
	global_load_dwordx4 v[144:147], v[82:83], off offset:128
	global_load_dwordx4 v[148:151], v[84:85], off
	global_load_dwordx4 v[152:155], v[92:93], off
	global_load_dwordx4 v[156:159], v[94:95], off
	global_load_dwordx4 v[160:163], v[96:97], off
	global_load_dwordx4 v[164:167], v[98:99], off
	global_load_dwordx4 v[168:171], v[100:101], off
	s_and_saveexec_b64 s[96:97], s[2:3]
	s_cbranch_execz .Lp3_rsK
	s_waitcnt vmcnt(16)
	v_add_f32_e32 v238, v238, v239
	v_add_f32_e32 v240, v240, v241
	v_add_f32_e32 v242, v242, v243
	v_add_f32_e32 v244, v244, v245
	v_add_f32_e32 v238, v238, v240
	v_add_f32_e32 v242, v242, v244
	v_add_f32_e32 v238, v238, v242
	v_fmamk_f32 v238, v238, 0x3b000000, v138
	v_mul_f32_e32 v239, 0x4b800000, v238
	v_cmp_gt_f32_e32 vcc, s66, v238
	s_nop 1
	v_cndmask_b32_e32 v238, v238, v239, vcc
	v_rsq_f32_e32 v238, v238
	s_nop 0
	v_mul_f32_e32 v239, 0x45800000, v238
	v_cndmask_b32_e32 v238, v238, v239, vcc
	ds_write_b32 v71, v238
.Lp3_rsK:
	s_or_b64 exec, exec, s[96:97]
	v_add_co_u32_e32 v108, vcc, s67, v80
	s_waitcnt lgkmcnt(0)
	s_nop 0
	v_addc_co_u32_e32 v109, vcc, 0, v81, vcc
	v_add_co_u32_e32 v110, vcc, s70, v82
	s_barrier
	s_nop 0
	v_addc_co_u32_e32 v111, vcc, 0, v83, vcc
	v_add_co_u32_e32 v112, vcc, s71, v80
	s_nop 1
	v_addc_co_u32_e32 v113, vcc, 0, v81, vcc
	s_waitcnt vmcnt(16)
	v_add_co_u32_e32 v114, vcc, s72, v82
	s_waitcnt vmcnt(15)
	ds_write_b128 v121, v[2:5] offset:16
	s_waitcnt vmcnt(14)
	ds_write_b128 v121, v[6:9] offset:36880
	s_waitcnt vmcnt(13)
	ds_write_b128 v121, v[10:13] offset:4624
	s_waitcnt vmcnt(12)
	ds_write_b128 v121, v[14:17] offset:41488
	s_waitcnt vmcnt(11)
	ds_write_b128 v121, v[18:21] offset:9232
	s_waitcnt vmcnt(10)
	ds_write_b128 v121, v[22:25] offset:46096
	s_waitcnt vmcnt(9)
	ds_write_b128 v121, v[26:29] offset:13840
	s_waitcnt vmcnt(8)
	ds_write_b128 v121, v[30:33] offset:50704
	v_addc_co_u32_e32 v115, vcc, 0, v83, vcc
	v_add_co_u32_e32 v116, vcc, s73, v80
	s_waitcnt lgkmcnt(0)
	s_nop 0
	v_addc_co_u32_e32 v117, vcc, 0, v81, vcc
	v_add_co_u32_e32 v118, vcc, s62, v82
	s_barrier
	s_nop 0
	v_addc_co_u32_e32 v119, vcc, 0, v83, vcc
	global_load_dwordx4 v[172:175], v[80:81], off offset:256
	global_load_dwordx4 v[176:179], v[82:83], off offset:256
	global_load_dwordx4 v[180:183], v[108:109], off offset:256
	global_load_dwordx4 v[184:187], v[110:111], off offset:256
	global_load_dwordx4 v[190:193], v[112:113], off offset:256
	global_load_dwordx4 v[194:197], v[114:115], off offset:256
	global_load_dwordx4 v[198:201], v[116:117], off offset:256
	global_load_dwordx4 v[202:205], v[118:119], off offset:256
	ds_read_b128 v[2:5], v124 offset:16
	ds_read_b128 v[206:209], v124 offset:48
	ds_read_b128 v[6:9], v124 offset:4624
	ds_read_b128 v[210:213], v124 offset:4656
	ds_read_b128 v[10:13], v126 offset:36880
	ds_read_b128 v[214:217], v126 offset:36912
	ds_read_b128 v[14:17], v126 offset:41488
	ds_read_b128 v[218:221], v126 offset:41520
	s_waitcnt lgkmcnt(3)
	v_mfma_f32_32x32x16_bf16 v[50:65], v[2:5], v[10:13], 0
	s_waitcnt lgkmcnt(1)
	v_mfma_f32_32x32x16_bf16 v[34:49], v[2:5], v[14:17], 0
	v_mfma_f32_32x32x16_bf16 v[18:33], v[6:9], v[10:13], 0
	v_mfma_f32_32x32x16_bf16 v[2:17], v[6:9], v[14:17], 0
	ds_read_b128 v[222:225], v124 offset:80
	ds_read_b128 v[226:229], v124 offset:4688
	ds_read_b128 v[230:233], v126 offset:36944
	ds_read_b128 v[234:237], v126 offset:41552
	s_waitcnt lgkmcnt(4)
	v_mfma_f32_32x32x16_bf16 v[2:17], v[210:213], v[218:221], v[2:17]
	v_mfma_f32_32x32x16_bf16 v[50:65], v[206:209], v[214:217], v[50:65]
	v_mfma_f32_32x32x16_bf16 v[34:49], v[206:209], v[218:221], v[34:49]
	v_mfma_f32_32x32x16_bf16 v[18:33], v[210:213], v[214:217], v[18:33]
	ds_read_b128 v[206:209], v124 offset:112
	ds_read_b128 v[210:213], v124 offset:4720
	ds_read_b128 v[214:217], v126 offset:36976
	ds_read_b128 v[218:221], v126 offset:41584
	s_waitcnt lgkmcnt(4)
	v_mfma_f32_32x32x16_bf16 v[2:17], v[226:229], v[234:237], v[2:17]
	v_mfma_f32_32x32x16_bf16 v[50:65], v[222:225], v[230:233], v[50:65]
	v_mfma_f32_32x32x16_bf16 v[34:49], v[222:225], v[234:237], v[34:49]
	v_mfma_f32_32x32x16_bf16 v[18:33], v[226:229], v[230:233], v[18:33]
	s_waitcnt lgkmcnt(0)
	v_mfma_f32_32x32x16_bf16 v[2:17], v[210:213], v[218:221], v[2:17]
	v_mfma_f32_32x32x16_bf16 v[50:65], v[206:209], v[214:217], v[50:65]
	v_mfma_f32_32x32x16_bf16 v[34:49], v[206:209], v[218:221], v[34:49]
	v_mfma_f32_32x32x16_bf16 v[18:33], v[210:213], v[214:217], v[18:33]
	s_waitcnt vmcnt(15)
	ds_write_b128 v121, v[140:143] offset:18448
	s_waitcnt vmcnt(14)
	ds_write_b128 v121, v[144:147] offset:55312
	s_waitcnt vmcnt(13)
	ds_write_b128 v121, v[148:151] offset:23056
	s_waitcnt vmcnt(12)
	ds_write_b128 v121, v[152:155] offset:59920
	s_waitcnt vmcnt(11)
	ds_write_b128 v121, v[156:159] offset:27664
	s_waitcnt vmcnt(10)
	ds_write_b128 v121, v[160:163] offset:64528
	s_waitcnt vmcnt(9)
	ds_write_b128 v121, v[164:167] offset:32272
	s_waitcnt vmcnt(8)
	ds_write_b128 v122, v[168:171] offset:32256
	s_waitcnt lgkmcnt(0)
	s_barrier
; template <bool SWAP, class Epi>
; DI void gemm_tile(const u16* __restrict__ A, int lda, const u16* __restrict__ Bt, int ldb, int K, int m0, int n0, char* smem, Epi&& epi) {
;     ...
;   for (int kt = 0; kt < KT; kt += 2) {
;     if (kt + 2 < KT) {
;       const int k0 = (kt + 2) << 6;
; #pragma unroll
;       for (int i = 0; i < 4; ++i) { ra0[i] = *(const u32x4*)(ag + (size_t)i * 32 * lda + k0); rb0[i] = *(const u32x4*)(bg + (size_t)i * 32 * ldb + k0); }
;     }
;     compute(0);
; #pragma unroll
;     for (int i = 0; i < 4; ++i) { *(u32x4*)(asw + 128 * 72 + 32 * i * 72) = ra1[i]; *(u32x4*)(bsw + 128 * 72 + 32 * i * 72) = rb1[i]; }
;     __syncthreads();
;     if (kt + 3 < KT) {
;       const int k0 = (kt + 3) << 6;
; #pragma unroll
;       for (int i = 0; i < 4; ++i) { ra1[i] = *(const u32x4*)(ag + (size_t)i * 32 * lda + k0); rb1[i] = *(const u32x4*)(bg + (size_t)i * 32 * ldb + k0); }
;     }
;     compute(1);
;     if (kt + 2 < KT) {
; #pragma unroll
;       for (int i = 0; i < 4; ++i) { *(u32x4*)(asw + 32 * i * 72) = ra0[i]; *(u32x4*)(bsw + 32 * i * 72) = rb0[i]; }
;     }
;     __syncthreads();
	global_load_dwordx4 v[140:143], v[80:81], off offset:384
	global_load_dwordx4 v[144:147], v[82:83], off offset:384
	global_load_dwordx4 v[148:151], v[108:109], off offset:384
	global_load_dwordx4 v[152:155], v[110:111], off offset:384
	global_load_dwordx4 v[156:159], v[112:113], off offset:384
	global_load_dwordx4 v[160:163], v[114:115], off offset:384
	global_load_dwordx4 v[164:167], v[116:117], off offset:384
	global_load_dwordx4 v[168:171], v[118:119], off offset:384
	ds_read_b128 v[206:209], v124 offset:18448
	ds_read_b128 v[210:213], v124 offset:18480
	ds_read_b128 v[214:217], v124 offset:23056
	ds_read_b128 v[218:221], v124 offset:23088
	ds_read_b128 v[222:225], v126 offset:55312
	ds_read_b128 v[226:229], v126 offset:55344
	ds_read_b128 v[230:233], v126 offset:59920
	ds_read_b128 v[234:237], v126 offset:59952
	s_waitcnt lgkmcnt(1)
	v_mfma_f32_32x32x16_bf16 v[2:17], v[214:217], v[230:233], v[2:17]
	v_mfma_f32_32x32x16_bf16 v[50:65], v[206:209], v[222:225], v[50:65]
	v_mfma_f32_32x32x16_bf16 v[34:49], v[206:209], v[230:233], v[34:49]
	v_mfma_f32_32x32x16_bf16 v[18:33], v[214:217], v[222:225], v[18:33]
	ds_read_b128 v[206:209], v124 offset:18512
	ds_read_b128 v[214:217], v124 offset:23120
	ds_read_b128 v[222:225], v126 offset:55376
	ds_read_b128 v[230:233], v126 offset:59984
	s_waitcnt lgkmcnt(4)
	v_mfma_f32_32x32x16_bf16 v[2:17], v[218:221], v[234:237], v[2:17]
	v_mfma_f32_32x32x16_bf16 v[50:65], v[210:213], v[226:229], v[50:65]
	v_mfma_f32_32x32x16_bf16 v[34:49], v[210:213], v[234:237], v[34:49]
	v_mfma_f32_32x32x16_bf16 v[18:33], v[218:221], v[226:229], v[18:33]
	ds_read_b128 v[210:213], v124 offset:18544
	ds_read_b128 v[218:221], v124 offset:23152
	ds_read_b128 v[226:229], v126 offset:55408
	ds_read_b128 v[234:237], v126 offset:60016
	s_waitcnt lgkmcnt(4)
	v_mfma_f32_32x32x16_bf16 v[2:17], v[214:217], v[230:233], v[2:17]
	v_mfma_f32_32x32x16_bf16 v[50:65], v[206:209], v[222:225], v[50:65]
	v_mfma_f32_32x32x16_bf16 v[34:49], v[206:209], v[230:233], v[34:49]
	v_mfma_f32_32x32x16_bf16 v[18:33], v[214:217], v[222:225], v[18:33]
	s_waitcnt lgkmcnt(0)
	v_mfma_f32_32x32x16_bf16 v[2:17], v[218:221], v[234:237], v[2:17]
	v_mfma_f32_32x32x16_bf16 v[50:65], v[210:213], v[226:229], v[50:65]
	v_mfma_f32_32x32x16_bf16 v[34:49], v[210:213], v[234:237], v[34:49]
	v_mfma_f32_32x32x16_bf16 v[18:33], v[218:221], v[226:229], v[18:33]
	s_waitcnt vmcnt(15)
	ds_write_b128 v121, v[172:175] offset:16
	s_waitcnt vmcnt(14)
	ds_write_b128 v121, v[176:179] offset:36880
	s_waitcnt vmcnt(13)
	ds_write_b128 v121, v[180:183] offset:4624
	s_waitcnt vmcnt(12)
	ds_write_b128 v121, v[184:187] offset:41488
	s_waitcnt vmcnt(11)
	ds_write_b128 v121, v[190:193] offset:9232
	s_waitcnt vmcnt(10)
	ds_write_b128 v121, v[194:197] offset:46096
	s_waitcnt vmcnt(9)
	ds_write_b128 v121, v[198:201] offset:13840
	s_waitcnt vmcnt(8)
	ds_write_b128 v121, v[202:205] offset:50704
	s_waitcnt lgkmcnt(0)
	s_barrier
	global_load_dwordx4 v[172:175], v[80:81], off offset:512
	global_load_dwordx4 v[176:179], v[82:83], off offset:512
	global_load_dwordx4 v[180:183], v[108:109], off offset:512
	global_load_dwordx4 v[184:187], v[110:111], off offset:512
	global_load_dwordx4 v[190:193], v[112:113], off offset:512
	global_load_dwordx4 v[194:197], v[114:115], off offset:512
	global_load_dwordx4 v[198:201], v[116:117], off offset:512
	global_load_dwordx4 v[202:205], v[118:119], off offset:512
	ds_read_b128 v[206:209], v124 offset:16
	ds_read_b128 v[210:213], v124 offset:48
	ds_read_b128 v[214:217], v124 offset:4624
	ds_read_b128 v[218:221], v124 offset:4656
	ds_read_b128 v[222:225], v126 offset:36880
	ds_read_b128 v[226:229], v126 offset:36912
	ds_read_b128 v[230:233], v126 offset:41488
	ds_read_b128 v[234:237], v126 offset:41520
	s_waitcnt lgkmcnt(1)
	v_mfma_f32_32x32x16_bf16 v[2:17], v[214:217], v[230:233], v[2:17]
	v_mfma_f32_32x32x16_bf16 v[50:65], v[206:209], v[222:225], v[50:65]
	v_mfma_f32_32x32x16_bf16 v[34:49], v[206:209], v[230:233], v[34:49]
	v_mfma_f32_32x32x16_bf16 v[18:33], v[214:217], v[222:225], v[18:33]
	ds_read_b128 v[206:209], v124 offset:80
	ds_read_b128 v[214:217], v124 offset:4688
	ds_read_b128 v[222:225], v126 offset:36944
	ds_read_b128 v[230:233], v126 offset:41552
	s_waitcnt lgkmcnt(4)
	v_mfma_f32_32x32x16_bf16 v[2:17], v[218:221], v[234:237], v[2:17]
	v_mfma_f32_32x32x16_bf16 v[50:65], v[210:213], v[226:229], v[50:65]
	v_mfma_f32_32x32x16_bf16 v[34:49], v[210:213], v[234:237], v[34:49]
	v_mfma_f32_32x32x16_bf16 v[18:33], v[218:221], v[226:229], v[18:33]
	ds_read_b128 v[210:213], v124 offset:112
	ds_read_b128 v[218:221], v124 offset:4720
	ds_read_b128 v[226:229], v126 offset:36976
	ds_read_b128 v[234:237], v126 offset:41584
	s_waitcnt lgkmcnt(4)
	v_mfma_f32_32x32x16_bf16 v[2:17], v[214:217], v[230:233], v[2:17]
	v_mfma_f32_32x32x16_bf16 v[50:65], v[206:209], v[222:225], v[50:65]
	v_mfma_f32_32x32x16_bf16 v[34:49], v[206:209], v[230:233], v[34:49]
	v_mfma_f32_32x32x16_bf16 v[18:33], v[214:217], v[222:225], v[18:33]
	s_waitcnt lgkmcnt(0)
	v_mfma_f32_32x32x16_bf16 v[2:17], v[218:221], v[234:237], v[2:17]
	v_mfma_f32_32x32x16_bf16 v[50:65], v[210:213], v[226:229], v[50:65]
	v_mfma_f32_32x32x16_bf16 v[34:49], v[210:213], v[234:237], v[34:49]
	v_mfma_f32_32x32x16_bf16 v[18:33], v[218:221], v[226:229], v[18:33]
	s_waitcnt vmcnt(15)
	ds_write_b128 v121, v[140:143] offset:18448
	s_waitcnt vmcnt(14)
	ds_write_b128 v121, v[144:147] offset:55312
	s_waitcnt vmcnt(13)
	ds_write_b128 v121, v[148:151] offset:23056
	s_waitcnt vmcnt(12)
	ds_write_b128 v121, v[152:155] offset:59920
	s_waitcnt vmcnt(11)
	ds_write_b128 v121, v[156:159] offset:27664
	s_waitcnt vmcnt(10)
	ds_write_b128 v121, v[160:163] offset:64528
	s_waitcnt vmcnt(9)
	ds_write_b128 v121, v[164:167] offset:32272
	s_waitcnt vmcnt(8)
	ds_write_b128 v122, v[168:171] offset:32256
	s_waitcnt lgkmcnt(0)
	s_barrier
; template <bool SWAP, class Epi>
; DI void gemm_tile(const u16* __restrict__ A, int lda, const u16* __restrict__ Bt, int ldb, int K, int m0, int n0, char* smem, Epi&& epi) {
;     ...
;   for (int kt = 0; kt < KT; kt += 2) {
;     if (kt + 2 < KT) {
;       const int k0 = (kt + 2) << 6;
; #pragma unroll
;       for (int i = 0; i < 4; ++i) { ra0[i] = *(const u32x4*)(ag + (size_t)i * 32 * lda + k0); rb0[i] = *(const u32x4*)(bg + (size_t)i * 32 * ldb + k0); }
;     }
;     compute(0);
; #pragma unroll
;     for (int i = 0; i < 4; ++i) { *(u32x4*)(asw + 128 * 72 + 32 * i * 72) = ra1[i]; *(u32x4*)(bsw + 128 * 72 + 32 * i * 72) = rb1[i]; }
;     __syncthreads();
;     if (kt + 3 < KT) {
;       const int k0 = (kt + 3) << 6;
; #pragma unroll
;       for (int i = 0; i < 4; ++i) { ra1[i] = *(const u32x4*)(ag + (size_t)i * 32 * lda + k0); rb1[i] = *(const u32x4*)(bg + (size_t)i * 32 * ldb + k0); }
;     }
;     compute(1);
;     if (kt + 2 < KT) {
; #pragma unroll
;       for (int i = 0; i < 4; ++i) { *(u32x4*)(asw + 32 * i * 72) = ra0[i]; *(u32x4*)(bsw + 32 * i * 72) = rb0[i]; }
;     }
;     __syncthreads();
	global_load_dwordx4 v[140:143], v[80:81], off offset:640
	global_load_dwordx4 v[144:147], v[82:83], off offset:640
	global_load_dwordx4 v[148:151], v[108:109], off offset:640
	global_load_dwordx4 v[152:155], v[110:111], off offset:640
	global_load_dwordx4 v[156:159], v[112:113], off offset:640
	global_load_dwordx4 v[160:163], v[114:115], off offset:640
	global_load_dwordx4 v[164:167], v[116:117], off offset:640
	global_load_dwordx4 v[168:171], v[118:119], off offset:640
	ds_read_b128 v[206:209], v124 offset:18448
	ds_read_b128 v[210:213], v124 offset:18480
	ds_read_b128 v[214:217], v124 offset:23056
	ds_read_b128 v[218:221], v124 offset:23088
	ds_read_b128 v[222:225], v126 offset:55312
	ds_read_b128 v[226:229], v126 offset:55344
	ds_read_b128 v[230:233], v126 offset:59920
	ds_read_b128 v[234:237], v126 offset:59952
	s_waitcnt lgkmcnt(1)
	v_mfma_f32_32x32x16_bf16 v[2:17], v[214:217], v[230:233], v[2:17]
	v_mfma_f32_32x32x16_bf16 v[50:65], v[206:209], v[222:225], v[50:65]
	v_mfma_f32_32x32x16_bf16 v[34:49], v[206:209], v[230:233], v[34:49]
	v_mfma_f32_32x32x16_bf16 v[18:33], v[214:217], v[222:225], v[18:33]
	ds_read_b128 v[206:209], v124 offset:18512
	ds_read_b128 v[214:217], v124 offset:23120
	ds_read_b128 v[222:225], v126 offset:55376
	ds_read_b128 v[230:233], v126 offset:59984
	s_waitcnt lgkmcnt(4)
	v_mfma_f32_32x32x16_bf16 v[2:17], v[218:221], v[234:237], v[2:17]
	v_mfma_f32_32x32x16_bf16 v[50:65], v[210:213], v[226:229], v[50:65]
	v_mfma_f32_32x32x16_bf16 v[34:49], v[210:213], v[234:237], v[34:49]
	v_mfma_f32_32x32x16_bf16 v[18:33], v[218:221], v[226:229], v[18:33]
	ds_read_b128 v[210:213], v124 offset:18544
	ds_read_b128 v[218:221], v124 offset:23152
	ds_read_b128 v[226:229], v126 offset:55408
	ds_read_b128 v[234:237], v126 offset:60016
	s_waitcnt lgkmcnt(4)
	v_mfma_f32_32x32x16_bf16 v[2:17], v[214:217], v[230:233], v[2:17]
	v_mfma_f32_32x32x16_bf16 v[50:65], v[206:209], v[222:225], v[50:65]
	v_mfma_f32_32x32x16_bf16 v[34:49], v[206:209], v[230:233], v[34:49]
	v_mfma_f32_32x32x16_bf16 v[18:33], v[214:217], v[222:225], v[18:33]
	s_waitcnt lgkmcnt(0)
	v_mfma_f32_32x32x16_bf16 v[2:17], v[218:221], v[234:237], v[2:17]
	v_mfma_f32_32x32x16_bf16 v[50:65], v[210:213], v[226:229], v[50:65]
	v_mfma_f32_32x32x16_bf16 v[34:49], v[210:213], v[234:237], v[34:49]
	v_mfma_f32_32x32x16_bf16 v[18:33], v[218:221], v[226:229], v[18:33]
	s_waitcnt vmcnt(15)
	ds_write_b128 v121, v[172:175] offset:16
	s_waitcnt vmcnt(14)
	ds_write_b128 v121, v[176:179] offset:36880
	s_waitcnt vmcnt(13)
	ds_write_b128 v121, v[180:183] offset:4624
	s_waitcnt vmcnt(12)
	ds_write_b128 v121, v[184:187] offset:41488
	s_waitcnt vmcnt(11)
	ds_write_b128 v121, v[190:193] offset:9232
	s_waitcnt vmcnt(10)
	ds_write_b128 v121, v[194:197] offset:46096
	s_waitcnt vmcnt(9)
	ds_write_b128 v121, v[198:201] offset:13840
	s_waitcnt vmcnt(8)
	ds_write_b128 v121, v[202:205] offset:50704
	s_waitcnt lgkmcnt(0)
	s_barrier
	global_load_dwordx4 v[172:175], v[80:81], off offset:768
	global_load_dwordx4 v[176:179], v[82:83], off offset:768
	global_load_dwordx4 v[180:183], v[108:109], off offset:768
	global_load_dwordx4 v[184:187], v[110:111], off offset:768
	global_load_dwordx4 v[190:193], v[112:113], off offset:768
	global_load_dwordx4 v[194:197], v[114:115], off offset:768
	global_load_dwordx4 v[198:201], v[116:117], off offset:768
	global_load_dwordx4 v[202:205], v[118:119], off offset:768
	ds_read_b128 v[206:209], v124 offset:16
	ds_read_b128 v[210:213], v124 offset:48
	ds_read_b128 v[214:217], v124 offset:4624
	ds_read_b128 v[218:221], v124 offset:4656
	ds_read_b128 v[222:225], v126 offset:36880
	ds_read_b128 v[226:229], v126 offset:36912
	ds_read_b128 v[230:233], v126 offset:41488
	ds_read_b128 v[234:237], v126 offset:41520
	s_waitcnt lgkmcnt(1)
	v_mfma_f32_32x32x16_bf16 v[2:17], v[214:217], v[230:233], v[2:17]
	v_mfma_f32_32x32x16_bf16 v[50:65], v[206:209], v[222:225], v[50:65]
	v_mfma_f32_32x32x16_bf16 v[34:49], v[206:209], v[230:233], v[34:49]
	v_mfma_f32_32x32x16_bf16 v[18:33], v[214:217], v[222:225], v[18:33]
	ds_read_b128 v[206:209], v124 offset:80
	ds_read_b128 v[214:217], v124 offset:4688
	ds_read_b128 v[222:225], v126 offset:36944
	ds_read_b128 v[230:233], v126 offset:41552
	s_waitcnt lgkmcnt(4)
	v_mfma_f32_32x32x16_bf16 v[2:17], v[218:221], v[234:237], v[2:17]
	v_mfma_f32_32x32x16_bf16 v[50:65], v[210:213], v[226:229], v[50:65]
	v_mfma_f32_32x32x16_bf16 v[34:49], v[210:213], v[234:237], v[34:49]
	v_mfma_f32_32x32x16_bf16 v[18:33], v[218:221], v[226:229], v[18:33]
	ds_read_b128 v[210:213], v124 offset:112
	ds_read_b128 v[218:221], v124 offset:4720
	ds_read_b128 v[226:229], v126 offset:36976
	ds_read_b128 v[234:237], v126 offset:41584
	s_waitcnt lgkmcnt(4)
	v_mfma_f32_32x32x16_bf16 v[2:17], v[214:217], v[230:233], v[2:17]
	v_mfma_f32_32x32x16_bf16 v[50:65], v[206:209], v[222:225], v[50:65]
	v_mfma_f32_32x32x16_bf16 v[34:49], v[206:209], v[230:233], v[34:49]
	v_mfma_f32_32x32x16_bf16 v[18:33], v[214:217], v[222:225], v[18:33]
	s_waitcnt lgkmcnt(0)
	v_mfma_f32_32x32x16_bf16 v[2:17], v[218:221], v[234:237], v[2:17]
	v_mfma_f32_32x32x16_bf16 v[50:65], v[210:213], v[226:229], v[50:65]
	v_mfma_f32_32x32x16_bf16 v[34:49], v[210:213], v[234:237], v[34:49]
	v_mfma_f32_32x32x16_bf16 v[18:33], v[218:221], v[226:229], v[18:33]
	s_waitcnt vmcnt(15)
	ds_write_b128 v121, v[140:143] offset:18448
	s_waitcnt vmcnt(14)
	ds_write_b128 v121, v[144:147] offset:55312
	s_waitcnt vmcnt(13)
	ds_write_b128 v121, v[148:151] offset:23056
	s_waitcnt vmcnt(12)
	ds_write_b128 v121, v[152:155] offset:59920
	s_waitcnt vmcnt(11)
	ds_write_b128 v121, v[156:159] offset:27664
	s_waitcnt vmcnt(10)
	ds_write_b128 v121, v[160:163] offset:64528
	s_waitcnt vmcnt(9)
	ds_write_b128 v121, v[164:167] offset:32272
	s_waitcnt vmcnt(8)
	ds_write_b128 v122, v[168:171] offset:32256
	s_waitcnt lgkmcnt(0)
	s_barrier
; template <bool SWAP, class Epi>
; DI void gemm_tile(const u16* __restrict__ A, int lda, const u16* __restrict__ Bt, int ldb, int K, int m0, int n0, char* smem, Epi&& epi) {
;     ...
;   for (int kt = 0; kt < KT; kt += 2) {
;     if (kt + 2 < KT) {
;       const int k0 = (kt + 2) << 6;
; #pragma unroll
;       for (int i = 0; i < 4; ++i) { ra0[i] = *(const u32x4*)(ag + (size_t)i * 32 * lda + k0); rb0[i] = *(const u32x4*)(bg + (size_t)i * 32 * ldb + k0); }
;     }
;     compute(0);
; #pragma unroll
;     for (int i = 0; i < 4; ++i) { *(u32x4*)(asw + 128 * 72 + 32 * i * 72) = ra1[i]; *(u32x4*)(bsw + 128 * 72 + 32 * i * 72) = rb1[i]; }
;     __syncthreads();
;     if (kt + 3 < KT) {
;       const int k0 = (kt + 3) << 6;
; #pragma unroll
;       for (int i = 0; i < 4; ++i) { ra1[i] = *(const u32x4*)(ag + (size_t)i * 32 * lda + k0); rb1[i] = *(const u32x4*)(bg + (size_t)i * 32 * ldb + k0); }
;     }
;     compute(1);
;     if (kt + 2 < KT) {
; #pragma unroll
;       for (int i = 0; i < 4; ++i) { *(u32x4*)(asw + 32 * i * 72) = ra0[i]; *(u32x4*)(bsw + 32 * i * 72) = rb0[i]; }
;     }
;     __syncthreads();
	global_load_dwordx4 v[140:143], v[80:81], off offset:896
	global_load_dwordx4 v[144:147], v[82:83], off offset:896
	global_load_dwordx4 v[148:151], v[108:109], off offset:896
	s_nop 0
	global_load_dwordx4 v[108:111], v[110:111], off offset:896
	s_nop 0
	global_load_dwordx4 v[152:155], v[112:113], off offset:896
	s_nop 0
	global_load_dwordx4 v[112:115], v[114:115], off offset:896
	s_nop 0
	global_load_dwordx4 v[156:159], v[116:117], off offset:896
	s_nop 0
	global_load_dwordx4 v[116:119], v[118:119], off offset:896
	ds_read_b128 v[160:163], v124 offset:18448
	ds_read_b128 v[164:167], v124 offset:18480
	ds_read_b128 v[168:171], v124 offset:23056
	ds_read_b128 v[206:209], v124 offset:23088
	ds_read_b128 v[210:213], v126 offset:55312
	ds_read_b128 v[214:217], v126 offset:55344
	ds_read_b128 v[218:221], v126 offset:59920
	ds_read_b128 v[222:225], v126 offset:59952
	s_waitcnt lgkmcnt(1)
	v_mfma_f32_32x32x16_bf16 v[2:17], v[168:171], v[218:221], v[2:17]
	v_mfma_f32_32x32x16_bf16 v[50:65], v[160:163], v[210:213], v[50:65]
	v_mfma_f32_32x32x16_bf16 v[34:49], v[160:163], v[218:221], v[34:49]
	v_mfma_f32_32x32x16_bf16 v[18:33], v[168:171], v[210:213], v[18:33]
	ds_read_b128 v[160:163], v124 offset:18512
	ds_read_b128 v[168:171], v124 offset:23120
	ds_read_b128 v[210:213], v126 offset:55376
	ds_read_b128 v[218:221], v126 offset:59984
	s_waitcnt lgkmcnt(4)
	v_mfma_f32_32x32x16_bf16 v[2:17], v[206:209], v[222:225], v[2:17]
	v_mfma_f32_32x32x16_bf16 v[50:65], v[164:167], v[214:217], v[50:65]
	v_mfma_f32_32x32x16_bf16 v[34:49], v[164:167], v[222:225], v[34:49]
	v_mfma_f32_32x32x16_bf16 v[18:33], v[206:209], v[214:217], v[18:33]
	ds_read_b128 v[164:167], v124 offset:18544
	ds_read_b128 v[206:209], v124 offset:23152
	ds_read_b128 v[214:217], v126 offset:55408
	ds_read_b128 v[222:225], v126 offset:60016
	s_waitcnt lgkmcnt(4)
	v_mfma_f32_32x32x16_bf16 v[2:17], v[168:171], v[218:221], v[2:17]
	v_mfma_f32_32x32x16_bf16 v[50:65], v[160:163], v[210:213], v[50:65]
	v_mfma_f32_32x32x16_bf16 v[34:49], v[160:163], v[218:221], v[34:49]
	v_mfma_f32_32x32x16_bf16 v[18:33], v[168:171], v[210:213], v[18:33]
	s_waitcnt lgkmcnt(0)
	v_mfma_f32_32x32x16_bf16 v[2:17], v[206:209], v[222:225], v[2:17]
	v_mfma_f32_32x32x16_bf16 v[50:65], v[164:167], v[214:217], v[50:65]
	v_mfma_f32_32x32x16_bf16 v[34:49], v[164:167], v[222:225], v[34:49]
	v_mfma_f32_32x32x16_bf16 v[18:33], v[206:209], v[214:217], v[18:33]
	s_waitcnt vmcnt(15)
	ds_write_b128 v121, v[172:175] offset:16
	s_waitcnt vmcnt(14)
	ds_write_b128 v121, v[176:179] offset:36880
	s_waitcnt vmcnt(13)
	ds_write_b128 v121, v[180:183] offset:4624
	s_waitcnt vmcnt(12)
	ds_write_b128 v121, v[184:187] offset:41488
	s_waitcnt vmcnt(11)
	ds_write_b128 v121, v[190:193] offset:9232
	s_waitcnt vmcnt(10)
	ds_write_b128 v121, v[194:197] offset:46096
	s_waitcnt vmcnt(9)
	ds_write_b128 v121, v[198:201] offset:13840
	s_waitcnt vmcnt(8)
	ds_write_b128 v121, v[202:205] offset:50704
	s_waitcnt lgkmcnt(0)
	s_barrier
	ds_read_b128 v[160:163], v124 offset:16
	ds_read_b128 v[164:167], v124 offset:48
	ds_read_b128 v[168:171], v124 offset:4624
	ds_read_b128 v[172:175], v124 offset:4656
	ds_read_b128 v[176:179], v126 offset:36880
	ds_read_b128 v[180:183], v126 offset:36912
	ds_read_b128 v[184:187], v126 offset:41488
	ds_read_b128 v[190:193], v126 offset:41520
	s_waitcnt lgkmcnt(1)
	v_mfma_f32_32x32x16_bf16 v[2:17], v[168:171], v[184:187], v[2:17]
	v_mfma_f32_32x32x16_bf16 v[50:65], v[160:163], v[176:179], v[50:65]
	v_mfma_f32_32x32x16_bf16 v[34:49], v[160:163], v[184:187], v[34:49]
	v_mfma_f32_32x32x16_bf16 v[18:33], v[168:171], v[176:179], v[18:33]
	ds_read_b128 v[160:163], v124 offset:80
	ds_read_b128 v[168:171], v124 offset:4688
	ds_read_b128 v[176:179], v126 offset:36944
	ds_read_b128 v[184:187], v126 offset:41552
	s_waitcnt lgkmcnt(4)
	v_mfma_f32_32x32x16_bf16 v[2:17], v[172:175], v[190:193], v[2:17]
	v_mfma_f32_32x32x16_bf16 v[50:65], v[164:167], v[180:183], v[50:65]
	v_mfma_f32_32x32x16_bf16 v[34:49], v[164:167], v[190:193], v[34:49]
	v_mfma_f32_32x32x16_bf16 v[18:33], v[172:175], v[180:183], v[18:33]
	ds_read_b128 v[164:167], v124 offset:112
	ds_read_b128 v[172:175], v124 offset:4720
	ds_read_b128 v[180:183], v126 offset:36976
	ds_read_b128 v[190:193], v126 offset:41584
	s_waitcnt lgkmcnt(4)
	v_mfma_f32_32x32x16_bf16 v[2:17], v[168:171], v[184:187], v[2:17]
	v_mfma_f32_32x32x16_bf16 v[50:65], v[160:163], v[176:179], v[50:65]
	v_mfma_f32_32x32x16_bf16 v[34:49], v[160:163], v[184:187], v[34:49]
	v_mfma_f32_32x32x16_bf16 v[18:33], v[168:171], v[176:179], v[18:33]
	s_waitcnt lgkmcnt(0)
	v_mfma_f32_32x32x16_bf16 v[2:17], v[172:175], v[190:193], v[2:17]
	v_mfma_f32_32x32x16_bf16 v[50:65], v[164:167], v[180:183], v[50:65]
	v_mfma_f32_32x32x16_bf16 v[34:49], v[164:167], v[190:193], v[34:49]
	v_mfma_f32_32x32x16_bf16 v[18:33], v[172:175], v[180:183], v[18:33]
	s_waitcnt vmcnt(7)
	ds_write_b128 v121, v[140:143] offset:18448
	s_waitcnt vmcnt(6)
	ds_write_b128 v121, v[144:147] offset:55312
	s_waitcnt vmcnt(5)
	ds_write_b128 v121, v[148:151] offset:23056
	s_waitcnt vmcnt(4)
	ds_write_b128 v121, v[108:111] offset:59920
	s_waitcnt vmcnt(3)
	ds_write_b128 v121, v[152:155] offset:27664
	s_waitcnt vmcnt(2)
	ds_write_b128 v121, v[112:115] offset:64528
	s_waitcnt vmcnt(1)
	ds_write_b128 v121, v[156:159] offset:32272
	s_waitcnt vmcnt(0)
	ds_write_b128 v122, v[116:119] offset:32256
	s_waitcnt lgkmcnt(0)
	s_barrier
; DI unsigned pk2(float a, float b) { f2_t v = {a, b}; bf2_t r = __builtin_convertvector(v, bf2_t); return __builtin_bit_cast(unsigned, r); }
; template <bool SWAP, class Epi>
; DI void gemm_tile(const u16* __restrict__ A, int lda, const u16* __restrict__ Bt, int ldb, int K, int m0, int n0, char* smem, Epi&& epi) {
;     ...
;     compute(1);
;     if (kt + 2 < KT) {
; #pragma unroll
;       for (int i = 0; i < 4; ++i) { *(u32x4*)(asw + 32 * i * 72) = ra0[i]; *(u32x4*)(bsw + 32 * i * 72) = rb0[i]; }
;     }
;     __syncthreads();
; DI void phase3(const Params& p, char* smem) {
;     ...
;         gemm_tile<false>(P + 3584, INC, (const u16*)(p.ws + WS_WUKVT), 512, 512, tm * 128, tn * 128, smem, [&](f32x16 (&acc)[2][2], int mb, int nb, int r, int hi) __attribute__((always_inline)) {
; #pragma unroll
;           for (int mi = 0; mi < 2; ++mi)
; #pragma unroll
;             for (int g = 0; g < 4; ++g) {
;               const int row0 = mb + mi * 32 + hi * 4 + 8 * g;
;               const float s0 = rs[row0 - tm * 128], s1 = rs[row0 + 1 - tm * 128], s2 = rs[row0 + 2 - tm * 128], s3 = rs[row0 + 3 - tm * 128];
;               const int b = row0 >> 11, t = row0 & (S_ - 1);
; #pragma unroll
;               for (int ni = 0; ni < 2; ++ni) {
;                 const int d = (nb & 127) + ni * 32 + r;
;                 *(uint2*)(VT + ((size_t)((b * 8 + head) * 128 + d)) * S_ + t) = make_uint2(pk2(acc[mi][ni][4 * g] * s0, acc[mi][ni][4 * g + 1] * s1), pk2(acc[mi][ni][4 * g + 2] * s2, acc[mi][ni][4 * g + 3] * s3));
;               }
;             }
;         });
	ds_read_b128 v[108:111], v124 offset:18448
	ds_read_b128 v[112:115], v124 offset:18480
	ds_read_b128 v[116:119], v124 offset:23056
	ds_read_b128 v[140:143], v124 offset:23088
	ds_read_b128 v[144:147], v126 offset:55312
	ds_read_b128 v[148:151], v126 offset:55344
	ds_read_b128 v[152:155], v126 offset:59920
	ds_read_b128 v[156:159], v126 offset:59952
	s_waitcnt lgkmcnt(1)
	v_mfma_f32_32x32x16_bf16 v[2:17], v[116:119], v[152:155], v[2:17]
	v_mfma_f32_32x32x16_bf16 v[50:65], v[108:111], v[144:147], v[50:65]
	v_mfma_f32_32x32x16_bf16 v[34:49], v[108:111], v[152:155], v[34:49]
	v_mfma_f32_32x32x16_bf16 v[18:33], v[116:119], v[144:147], v[18:33]
	ds_read_b128 v[108:111], v124 offset:18512
	ds_read_b128 v[116:119], v124 offset:23120
	ds_read_b128 v[144:147], v126 offset:55376
	ds_read_b128 v[152:155], v126 offset:59984
	s_waitcnt lgkmcnt(4)
	v_mfma_f32_32x32x16_bf16 v[2:17], v[140:143], v[156:159], v[2:17]
	v_mfma_f32_32x32x16_bf16 v[50:65], v[112:115], v[148:151], v[50:65]
	v_mfma_f32_32x32x16_bf16 v[34:49], v[112:115], v[156:159], v[34:49]
	v_mfma_f32_32x32x16_bf16 v[18:33], v[140:143], v[148:151], v[18:33]
	ds_read_b128 v[112:115], v124 offset:18544
	ds_read_b128 v[140:143], v124 offset:23152
	ds_read_b128 v[148:151], v126 offset:55408
	ds_read_b128 v[156:159], v126 offset:60016
	s_waitcnt lgkmcnt(4)
	v_mfma_f32_32x32x16_bf16 v[2:17], v[116:119], v[152:155], v[2:17]
	v_mfma_f32_32x32x16_bf16 v[50:65], v[108:111], v[144:147], v[50:65]
	v_mfma_f32_32x32x16_bf16 v[34:49], v[108:111], v[152:155], v[34:49]
	v_mfma_f32_32x32x16_bf16 v[18:33], v[116:119], v[144:147], v[18:33]
	s_waitcnt lgkmcnt(0)
	v_mfma_f32_32x32x16_bf16 v[2:17], v[140:143], v[156:159], v[2:17]
	v_mfma_f32_32x32x16_bf16 v[50:65], v[112:115], v[148:151], v[50:65]
	v_mfma_f32_32x32x16_bf16 v[34:49], v[112:115], v[156:159], v[34:49]
	v_mfma_f32_32x32x16_bf16 v[18:33], v[140:143], v[148:151], v[18:33]
	s_barrier
	ds_read_b128 v[108:111], v128
	v_add_u32_e32 v79, s92, v127
	v_or_b32_e32 v112, 8, v79
	v_subrev_u32_e32 v112, s92, v112
	v_lshl_add_u32 v112, v112, 2, s54
	v_lshrrev_b32_e32 v66, 8, v79
	ds_read_b128 v[112:115], v112
	s_waitcnt lgkmcnt(1)
	s_nop 0
	v_pk_mul_f32 v[50:51], v[50:51], v[108:109]
	v_and_b32_e32 v66, 56, v66
	v_cvt_pk_bf16_f32 v116, v50, v51
	v_pk_mul_f32 v[50:51], v[52:53], v[110:111]
	v_pk_mul_f32 v[34:35], v[34:35], v[108:109]
	v_cvt_pk_bf16_f32 v117, v50, v51
	v_add_u32_e32 v50, s16, v66
	v_lshl_or_b32 v66, v50, 7, v125
	v_lshlrev_b64 v[50:51], 12, v[66:67]
	v_cvt_pk_bf16_f32 v108, v34, v35
	v_pk_mul_f32 v[34:35], v[36:37], v[110:111]
	v_or_b32_e32 v66, 32, v66
	v_and_b32_e32 v118, 0x7c4, v79
	v_cvt_pk_bf16_f32 v109, v34, v35
	v_lshlrev_b64 v[34:35], 12, v[66:67]
	v_lshlrev_b32_e32 v52, 1, v118
	v_mov_b32_e32 v53, v67
	v_lshl_add_u64 v[34:35], s[10:11], 0, v[34:35]
	v_lshl_add_u64 v[50:51], s[10:11], 0, v[50:51]
	v_lshl_add_u64 v[36:37], v[34:35], 0, v[52:53]
	v_bitop3_b32 v66, v79, s84, 8 bitop3:0xc8
	v_lshl_add_u64 v[118:119], v[50:51], 0, v[52:53]
	global_store_dwordx2 v[36:37], v[108:109], off
	s_waitcnt lgkmcnt(0)
	v_pk_mul_f32 v[36:37], v[54:55], v[112:113]
	v_pk_mul_f32 v[52:53], v[56:57], v[114:115]
	v_lshlrev_b32_e32 v66, 1, v66
	v_cvt_pk_bf16_f32 v36, v36, v37
	v_cvt_pk_bf16_f32 v37, v52, v53
	v_lshl_add_u64 v[52:53], v[50:51], 0, v[66:67]
	global_store_dwordx2 v[118:119], v[116:117], off
	global_store_dwordx2 v[52:53], v[36:37], off
	v_pk_mul_f32 v[36:37], v[38:39], v[112:113]
	v_pk_mul_f32 v[38:39], v[40:41], v[114:115]
	v_cvt_pk_bf16_f32 v36, v36, v37
	v_cvt_pk_bf16_f32 v37, v38, v39
	v_lshl_add_u64 v[38:39], v[34:35], 0, v[66:67]
	global_store_dwordx2 v[38:39], v[36:37], off
	v_or_b32_e32 v36, 16, v79
	v_subrev_u32_e32 v36, s92, v36
	v_lshl_add_u32 v36, v36, 2, s54
	ds_read_b128 v[36:39], v36
	v_or_b32_e32 v40, 24, v79
	v_subrev_u32_e32 v40, s92, v40
	v_lshl_add_u32 v40, v40, 2, s54
	ds_read_b128 v[52:55], v40
	v_bitop3_b32 v66, v79, s85, 16 bitop3:0xc8
	s_waitcnt lgkmcnt(1)
	v_pk_mul_f32 v[40:41], v[58:59], v[36:37]
	v_pk_mul_f32 v[56:57], v[60:61], v[38:39]
	v_lshlrev_b32_e32 v66, 1, v66
	v_cvt_pk_bf16_f32 v40, v40, v41
	v_cvt_pk_bf16_f32 v41, v56, v57
	v_lshl_add_u64 v[56:57], v[50:51], 0, v[66:67]
	v_pk_mul_f32 v[36:37], v[42:43], v[36:37]
	v_pk_mul_f32 v[38:39], v[44:45], v[38:39]
	global_store_dwordx2 v[56:57], v[40:41], off
	v_cvt_pk_bf16_f32 v36, v36, v37
	v_cvt_pk_bf16_f32 v37, v38, v39
	v_lshl_add_u64 v[38:39], v[34:35], 0, v[66:67]
	v_bitop3_b32 v40, v79, s86, 24 bitop3:0xc8
	global_store_dwordx2 v[38:39], v[36:37], off
	s_waitcnt lgkmcnt(0)
	v_pk_mul_f32 v[36:37], v[62:63], v[52:53]
	v_pk_mul_f32 v[38:39], v[64:65], v[54:55]
	v_lshlrev_b32_e32 v66, 1, v40
	v_cvt_pk_bf16_f32 v36, v36, v37
	v_cvt_pk_bf16_f32 v37, v38, v39
	v_lshl_add_u64 v[38:39], v[50:51], 0, v[66:67]
	global_store_dwordx2 v[38:39], v[36:37], off
	v_pk_mul_f32 v[36:37], v[46:47], v[52:53]
	v_pk_mul_f32 v[38:39], v[48:49], v[54:55]
	v_cvt_pk_bf16_f32 v36, v36, v37
	v_cvt_pk_bf16_f32 v37, v38, v39
	v_lshl_add_u64 v[38:39], v[34:35], 0, v[66:67]
	global_store_dwordx2 v[38:39], v[36:37], off
	v_or_b32_e32 v36, 32, v79
	v_subrev_u32_e32 v36, s92, v36
	v_lshl_add_u32 v36, v36, 2, s54
	ds_read_b128 v[36:39], v36
	v_or_b32_e32 v40, 40, v79
	v_subrev_u32_e32 v40, s92, v40
	v_lshl_add_u32 v40, v40, 2, s54
	ds_read_b128 v[40:43], v40
	v_bitop3_b32 v44, v79, s87, 32 bitop3:0xc8
	s_waitcnt lgkmcnt(1)
; DI unsigned pk2(float a, float b) { f2_t v = {a, b}; bf2_t r = __builtin_convertvector(v, bf2_t); return __builtin_bit_cast(unsigned, r); }
; DI void phase3(const Params& p, char* smem) {
;     ...
;       const int tn = it / 64, tm = it % 64;
;       __syncthreads();
;       if (threadIdx.x < 128) { const float4* sp = (const float4*)(SSQ + (size_t)(tm * 128 + threadIdx.x) * 16); const float4 a = sp[0], b = sp[1]; rs[threadIdx.x] = rsqrtf((((a.x + a.y) + (a.z + a.w)) + ((b.x + b.y) + (b.z + b.w))) * (1.f / 512.f) + EPS); }
;       gemm_tile<true>(P + 3072, INC, (const u16*)(p.ws + WS_WUQT), 512, 512, tm * 128, tn * 128, smem, [&](f32x16 (&acc)[2][2], int mb, int nb, int r, int hi) __attribute__((always_inline)) {
;     ...
;             for (int g = 0; g < 4; ++g) {
;               const int row0 = mb + mi * 32 + hi * 4 + 8 * g;
;               const float s0 = rs[row0 - tm * 128], s1 = rs[row0 + 1 - tm * 128], s2 = rs[row0 + 2 - tm * 128], s3 = rs[row0 + 3 - tm * 128];
;               const int b = row0 >> 11, t = row0 & (S_ - 1);
; #pragma unroll
;               for (int ni = 0; ni < 2; ++ni) {
;                 const int d = (nb & 127) + ni * 32 + r;
;                 *(uint2*)(VT + ((size_t)((b * 8 + head) * 128 + d)) * S_ + t) = make_uint2(pk2(acc[mi][ni][4 * g] * s0, acc[mi][ni][4 * g + 1] * s1), pk2(acc[mi][ni][4 * g + 2] * s2, acc[mi][ni][4 * g + 3] * s3));
;               }
;             }
;         });
	v_pk_mul_f32 v[18:19], v[18:19], v[36:37]
	v_pk_mul_f32 v[20:21], v[20:21], v[38:39]
	v_lshlrev_b32_e32 v66, 1, v44
	v_cvt_pk_bf16_f32 v18, v18, v19
	v_cvt_pk_bf16_f32 v19, v20, v21
	v_lshl_add_u64 v[20:21], v[50:51], 0, v[66:67]
	v_pk_mul_f32 v[2:3], v[2:3], v[36:37]
	v_pk_mul_f32 v[4:5], v[4:5], v[38:39]
	global_store_dwordx2 v[20:21], v[18:19], off
	v_cvt_pk_bf16_f32 v2, v2, v3
	v_cvt_pk_bf16_f32 v3, v4, v5
	v_lshl_add_u64 v[4:5], v[34:35], 0, v[66:67]
	v_bitop3_b32 v18, v79, s88, 40 bitop3:0xc8
	global_store_dwordx2 v[4:5], v[2:3], off
	s_waitcnt lgkmcnt(0)
	v_pk_mul_f32 v[2:3], v[22:23], v[40:41]
	v_pk_mul_f32 v[4:5], v[24:25], v[42:43]
	v_lshlrev_b32_e32 v66, 1, v18
	v_cvt_pk_bf16_f32 v2, v2, v3
	v_cvt_pk_bf16_f32 v3, v4, v5
	v_lshl_add_u64 v[4:5], v[50:51], 0, v[66:67]
	global_store_dwordx2 v[4:5], v[2:3], off
	v_pk_mul_f32 v[2:3], v[6:7], v[40:41]
	v_pk_mul_f32 v[4:5], v[8:9], v[42:43]
	v_cvt_pk_bf16_f32 v2, v2, v3
	v_cvt_pk_bf16_f32 v3, v4, v5
	v_lshl_add_u64 v[4:5], v[34:35], 0, v[66:67]
	global_store_dwordx2 v[4:5], v[2:3], off
	v_or_b32_e32 v2, 48, v79
	v_subrev_u32_e32 v2, s92, v2
	v_lshl_add_u32 v2, v2, 2, s54
	v_or_b32_e32 v6, 56, v79
	ds_read_b128 v[2:5], v2
	v_subrev_u32_e32 v6, s92, v6
	v_lshl_add_u32 v6, v6, 2, s54
	ds_read_b128 v[6:9], v6
	v_bitop3_b32 v22, v79, s89, 48 bitop3:0xc8
	s_waitcnt lgkmcnt(1)
	v_pk_mul_f32 v[18:19], v[26:27], v[2:3]
	v_pk_mul_f32 v[20:21], v[28:29], v[4:5]
	v_lshlrev_b32_e32 v66, 1, v22
	v_pk_mul_f32 v[2:3], v[10:11], v[2:3]
	v_pk_mul_f32 v[4:5], v[12:13], v[4:5]
	v_cvt_pk_bf16_f32 v2, v2, v3
	v_cvt_pk_bf16_f32 v3, v4, v5
	v_lshl_add_u64 v[4:5], v[34:35], 0, v[66:67]
	v_bitop3_b32 v10, v79, s90, 56 bitop3:0xc8
	v_cvt_pk_bf16_f32 v18, v18, v19
	v_cvt_pk_bf16_f32 v19, v20, v21
	v_lshl_add_u64 v[20:21], v[50:51], 0, v[66:67]
	global_store_dwordx2 v[4:5], v[2:3], off
	s_waitcnt lgkmcnt(0)
	v_pk_mul_f32 v[2:3], v[30:31], v[6:7]
	v_pk_mul_f32 v[4:5], v[32:33], v[8:9]
	v_lshlrev_b32_e32 v66, 1, v10
	v_cvt_pk_bf16_f32 v2, v2, v3
	v_cvt_pk_bf16_f32 v3, v4, v5
	v_lshl_add_u64 v[4:5], v[50:51], 0, v[66:67]
	global_store_dwordx2 v[20:21], v[18:19], off
	global_store_dwordx2 v[4:5], v[2:3], off
	v_pk_mul_f32 v[2:3], v[14:15], v[6:7]
	v_pk_mul_f32 v[4:5], v[16:17], v[8:9]
	v_cvt_pk_bf16_f32 v2, v2, v3
	v_lshl_add_u64 v[8:9], v[34:35], 0, v[66:67]
	global_store_dword v[8:9], v2, off
	s_mov_b64 s[50:51], 0
	v_mov_b32_e32 v6, v5
.LBB0_513:
	s_andn2_b64 vcc, exec, s[50:51]
	s_cbranch_vccnz .LBB0_515
	global_load_dwordx4 v[2:5], v[80:81], off
	global_load_dwordx4 v[6:9], v[82:83], off
	global_load_dwordx4 v[10:13], v[90:91], off
	global_load_dwordx4 v[14:17], v[106:107], off
	global_load_dwordx4 v[18:21], v[88:89], off
	global_load_dwordx4 v[22:25], v[104:105], off
	global_load_dwordx4 v[26:29], v[86:87], off
	global_load_dwordx4 v[30:33], v[102:103], off
	s_nop 0
	global_load_dwordx4 v[102:105], v[80:81], off offset:128
	global_load_dwordx4 v[106:109], v[82:83], off offset:128
	global_load_dwordx4 v[110:113], v[84:85], off
	global_load_dwordx4 v[114:117], v[92:93], off
	global_load_dwordx4 v[140:143], v[94:95], off
	global_load_dwordx4 v[144:147], v[96:97], off
	s_nop 0
	global_load_dwordx4 v[96:99], v[98:99], off
	s_nop 0
	global_load_dwordx4 v[148:151], v[100:101], off
	s_and_saveexec_b64 s[96:97], s[2:3]
	s_cbranch_execz .Lp3_rsV
	s_waitcnt vmcnt(16)
	v_add_f32_e32 v238, v238, v239
	v_add_f32_e32 v240, v240, v241
	v_add_f32_e32 v242, v242, v243
	v_add_f32_e32 v244, v244, v245
	v_add_f32_e32 v238, v238, v240
	v_add_f32_e32 v242, v242, v244
	v_add_f32_e32 v238, v238, v242
	v_fmamk_f32 v238, v238, 0x3b000000, v138
	v_mul_f32_e32 v239, 0x4b800000, v238
	v_cmp_gt_f32_e32 vcc, s66, v238
	s_nop 1
	v_cndmask_b32_e32 v238, v238, v239, vcc
	v_rsq_f32_e32 v238, v238
	s_nop 0
	v_mul_f32_e32 v239, 0x45800000, v238
	v_cndmask_b32_e32 v238, v238, v239, vcc
	ds_write_b32 v71, v238
.Lp3_rsV:
	s_or_b64 exec, exec, s[96:97]
	v_add_co_u32_e32 v84, vcc, s67, v80
	s_waitcnt lgkmcnt(0)
	s_nop 0
	v_addc_co_u32_e32 v85, vcc, 0, v81, vcc
	v_add_co_u32_e32 v86, vcc, s70, v82
	s_barrier
	s_nop 0
	v_addc_co_u32_e32 v87, vcc, 0, v83, vcc
	v_add_co_u32_e32 v88, vcc, s71, v80
	s_nop 1
	v_addc_co_u32_e32 v89, vcc, 0, v81, vcc
	v_add_co_u32_e32 v90, vcc, s72, v82
	s_waitcnt vmcnt(15)
	ds_write_b128 v121, v[2:5] offset:16
	s_waitcnt vmcnt(14)
	ds_write_b128 v121, v[6:9] offset:36880
	s_waitcnt vmcnt(13)
	ds_write_b128 v121, v[10:13] offset:4624
	s_waitcnt vmcnt(12)
	ds_write_b128 v121, v[14:17] offset:41488
	s_waitcnt vmcnt(11)
	ds_write_b128 v121, v[18:21] offset:9232
	s_waitcnt vmcnt(10)
	ds_write_b128 v121, v[22:25] offset:46096
	s_waitcnt vmcnt(9)
	ds_write_b128 v121, v[26:29] offset:13840
	s_waitcnt vmcnt(8)
	ds_write_b128 v121, v[30:33] offset:50704
	v_addc_co_u32_e32 v91, vcc, 0, v83, vcc
	v_add_co_u32_e32 v92, vcc, s73, v80
	s_waitcnt lgkmcnt(0)
	s_nop 0
	v_addc_co_u32_e32 v93, vcc, 0, v81, vcc
	v_add_co_u32_e32 v94, vcc, s62, v82
	s_barrier
; template <bool SWAP, class Epi>
; DI void gemm_tile(const u16* __restrict__ A, int lda, const u16* __restrict__ Bt, int ldb, int K, int m0, int n0, char* smem, Epi&& epi) {
;     ...
;   for (int kt = 0; kt < KT; kt += 2) {
;     if (kt + 2 < KT) {
;       const int k0 = (kt + 2) << 6;
; #pragma unroll
;       for (int i = 0; i < 4; ++i) { ra0[i] = *(const u32x4*)(ag + (size_t)i * 32 * lda + k0); rb0[i] = *(const u32x4*)(bg + (size_t)i * 32 * ldb + k0); }
;     }
;     compute(0);
; #pragma unroll
;     for (int i = 0; i < 4; ++i) { *(u32x4*)(asw + 128 * 72 + 32 * i * 72) = ra1[i]; *(u32x4*)(bsw + 128 * 72 + 32 * i * 72) = rb1[i]; }
;     __syncthreads();
;     if (kt + 3 < KT) {
;       const int k0 = (kt + 3) << 6;
; #pragma unroll
;       for (int i = 0; i < 4; ++i) { ra1[i] = *(const u32x4*)(ag + (size_t)i * 32 * lda + k0); rb1[i] = *(const u32x4*)(bg + (size_t)i * 32 * ldb + k0); }
;     }
;     compute(1);
;     if (kt + 2 < KT) {
; #pragma unroll
;       for (int i = 0; i < 4; ++i) { *(u32x4*)(asw + 32 * i * 72) = ra0[i]; *(u32x4*)(bsw + 32 * i * 72) = rb0[i]; }
;     }
;     __syncthreads();
	s_nop 0
	v_addc_co_u32_e32 v95, vcc, 0, v83, vcc
	global_load_dwordx4 v[152:155], v[80:81], off offset:256
	global_load_dwordx4 v[156:159], v[82:83], off offset:256
	global_load_dwordx4 v[160:163], v[84:85], off offset:256
	global_load_dwordx4 v[164:167], v[86:87], off offset:256
	global_load_dwordx4 v[168:171], v[88:89], off offset:256
	global_load_dwordx4 v[172:175], v[90:91], off offset:256
	global_load_dwordx4 v[176:179], v[92:93], off offset:256
	global_load_dwordx4 v[180:183], v[94:95], off offset:256
	ds_read_b128 v[2:5], v124 offset:16
	ds_read_b128 v[184:187], v124 offset:48
	ds_read_b128 v[6:9], v124 offset:4624
	ds_read_b128 v[190:193], v124 offset:4656
	ds_read_b128 v[10:13], v126 offset:36880
	ds_read_b128 v[194:197], v126 offset:36912
	ds_read_b128 v[14:17], v126 offset:41488
	ds_read_b128 v[198:201], v126 offset:41520
	s_waitcnt lgkmcnt(3)
	v_mfma_f32_32x32x16_bf16 v[50:65], v[10:13], v[2:5], 0
	s_waitcnt lgkmcnt(1)
	v_mfma_f32_32x32x16_bf16 v[34:49], v[14:17], v[2:5], 0
	v_mfma_f32_32x32x16_bf16 v[18:33], v[10:13], v[6:9], 0
	v_mfma_f32_32x32x16_bf16 v[2:17], v[14:17], v[6:9], 0
	ds_read_b128 v[202:205], v124 offset:80
	ds_read_b128 v[206:209], v124 offset:4688
	ds_read_b128 v[210:213], v126 offset:36944
	ds_read_b128 v[214:217], v126 offset:41552
	s_waitcnt lgkmcnt(4)
	v_mfma_f32_32x32x16_bf16 v[2:17], v[198:201], v[190:193], v[2:17]
	v_mfma_f32_32x32x16_bf16 v[50:65], v[194:197], v[184:187], v[50:65]
	v_mfma_f32_32x32x16_bf16 v[34:49], v[198:201], v[184:187], v[34:49]
	v_mfma_f32_32x32x16_bf16 v[18:33], v[194:197], v[190:193], v[18:33]
	ds_read_b128 v[184:187], v124 offset:112
	ds_read_b128 v[190:193], v124 offset:4720
	ds_read_b128 v[194:197], v126 offset:36976
	ds_read_b128 v[198:201], v126 offset:41584
	s_waitcnt lgkmcnt(4)
	v_mfma_f32_32x32x16_bf16 v[2:17], v[214:217], v[206:209], v[2:17]
	v_mfma_f32_32x32x16_bf16 v[50:65], v[210:213], v[202:205], v[50:65]
	v_mfma_f32_32x32x16_bf16 v[34:49], v[214:217], v[202:205], v[34:49]
	v_mfma_f32_32x32x16_bf16 v[18:33], v[210:213], v[206:209], v[18:33]
	s_waitcnt lgkmcnt(0)
	v_mfma_f32_32x32x16_bf16 v[2:17], v[198:201], v[190:193], v[2:17]
	v_mfma_f32_32x32x16_bf16 v[50:65], v[194:197], v[184:187], v[50:65]
	v_mfma_f32_32x32x16_bf16 v[34:49], v[198:201], v[184:187], v[34:49]
	v_mfma_f32_32x32x16_bf16 v[18:33], v[194:197], v[190:193], v[18:33]
	s_waitcnt vmcnt(15)
	ds_write_b128 v121, v[102:105] offset:18448
	s_waitcnt vmcnt(14)
	ds_write_b128 v121, v[106:109] offset:55312
	s_waitcnt vmcnt(13)
	ds_write_b128 v121, v[110:113] offset:23056
	s_waitcnt vmcnt(12)
	ds_write_b128 v121, v[114:117] offset:59920
	s_waitcnt vmcnt(11)
	ds_write_b128 v121, v[140:143] offset:27664
	s_waitcnt vmcnt(10)
	ds_write_b128 v121, v[144:147] offset:64528
	s_waitcnt vmcnt(9)
	ds_write_b128 v121, v[96:99] offset:32272
	s_waitcnt vmcnt(8)
	ds_write_b128 v122, v[148:151] offset:32256
	s_waitcnt lgkmcnt(0)
	s_barrier
	global_load_dwordx4 v[96:99], v[80:81], off offset:384
	global_load_dwordx4 v[100:103], v[82:83], off offset:384
	global_load_dwordx4 v[104:107], v[84:85], off offset:384
	global_load_dwordx4 v[108:111], v[86:87], off offset:384
	global_load_dwordx4 v[112:115], v[88:89], off offset:384
	global_load_dwordx4 v[116:119], v[90:91], off offset:384
	global_load_dwordx4 v[140:143], v[92:93], off offset:384
	global_load_dwordx4 v[144:147], v[94:95], off offset:384
	ds_read_b128 v[148:151], v124 offset:18448
	ds_read_b128 v[184:187], v124 offset:18480
	ds_read_b128 v[190:193], v124 offset:23056
	ds_read_b128 v[194:197], v124 offset:23088
	ds_read_b128 v[198:201], v126 offset:55312
	ds_read_b128 v[202:205], v126 offset:55344
	ds_read_b128 v[206:209], v126 offset:59920
	ds_read_b128 v[210:213], v126 offset:59952
	s_waitcnt lgkmcnt(1)
	v_mfma_f32_32x32x16_bf16 v[2:17], v[206:209], v[190:193], v[2:17]
	v_mfma_f32_32x32x16_bf16 v[50:65], v[198:201], v[148:151], v[50:65]
	v_mfma_f32_32x32x16_bf16 v[34:49], v[206:209], v[148:151], v[34:49]
	v_mfma_f32_32x32x16_bf16 v[18:33], v[198:201], v[190:193], v[18:33]
	ds_read_b128 v[148:151], v124 offset:18512
	ds_read_b128 v[190:193], v124 offset:23120
	ds_read_b128 v[198:201], v126 offset:55376
	ds_read_b128 v[206:209], v126 offset:59984
	s_waitcnt lgkmcnt(4)
	v_mfma_f32_32x32x16_bf16 v[2:17], v[210:213], v[194:197], v[2:17]
	v_mfma_f32_32x32x16_bf16 v[50:65], v[202:205], v[184:187], v[50:65]
	v_mfma_f32_32x32x16_bf16 v[34:49], v[210:213], v[184:187], v[34:49]
	v_mfma_f32_32x32x16_bf16 v[18:33], v[202:205], v[194:197], v[18:33]
	ds_read_b128 v[184:187], v124 offset:18544
	ds_read_b128 v[194:197], v124 offset:23152
	ds_read_b128 v[202:205], v126 offset:55408
	ds_read_b128 v[210:213], v126 offset:60016
	s_waitcnt lgkmcnt(4)
	v_mfma_f32_32x32x16_bf16 v[2:17], v[206:209], v[190:193], v[2:17]
	v_mfma_f32_32x32x16_bf16 v[50:65], v[198:201], v[148:151], v[50:65]
	v_mfma_f32_32x32x16_bf16 v[34:49], v[206:209], v[148:151], v[34:49]
	v_mfma_f32_32x32x16_bf16 v[18:33], v[198:201], v[190:193], v[18:33]
	s_waitcnt lgkmcnt(0)
	v_mfma_f32_32x32x16_bf16 v[2:17], v[210:213], v[194:197], v[2:17]
	v_mfma_f32_32x32x16_bf16 v[50:65], v[202:205], v[184:187], v[50:65]
	v_mfma_f32_32x32x16_bf16 v[34:49], v[210:213], v[184:187], v[34:49]
	v_mfma_f32_32x32x16_bf16 v[18:33], v[202:205], v[194:197], v[18:33]
	s_waitcnt vmcnt(15)
	ds_write_b128 v121, v[152:155] offset:16
	s_waitcnt vmcnt(14)
	ds_write_b128 v121, v[156:159] offset:36880
	s_waitcnt vmcnt(13)
	ds_write_b128 v121, v[160:163] offset:4624
	s_waitcnt vmcnt(12)
	ds_write_b128 v121, v[164:167] offset:41488
	s_waitcnt vmcnt(11)
	ds_write_b128 v121, v[168:171] offset:9232
	s_waitcnt vmcnt(10)
	ds_write_b128 v121, v[172:175] offset:46096
	s_waitcnt vmcnt(9)
	ds_write_b128 v121, v[176:179] offset:13840
	s_waitcnt vmcnt(8)
	ds_write_b128 v121, v[180:183] offset:50704
	s_waitcnt lgkmcnt(0)
	s_barrier
; template <bool SWAP, class Epi>
; DI void gemm_tile(const u16* __restrict__ A, int lda, const u16* __restrict__ Bt, int ldb, int K, int m0, int n0, char* smem, Epi&& epi) {
;     ...
;   for (int kt = 0; kt < KT; kt += 2) {
;     if (kt + 2 < KT) {
;       const int k0 = (kt + 2) << 6;
; #pragma unroll
;       for (int i = 0; i < 4; ++i) { ra0[i] = *(const u32x4*)(ag + (size_t)i * 32 * lda + k0); rb0[i] = *(const u32x4*)(bg + (size_t)i * 32 * ldb + k0); }
;     }
;     compute(0);
; #pragma unroll
;     for (int i = 0; i < 4; ++i) { *(u32x4*)(asw + 128 * 72 + 32 * i * 72) = ra1[i]; *(u32x4*)(bsw + 128 * 72 + 32 * i * 72) = rb1[i]; }
;     __syncthreads();
;     if (kt + 3 < KT) {
;       const int k0 = (kt + 3) << 6;
; #pragma unroll
;       for (int i = 0; i < 4; ++i) { ra1[i] = *(const u32x4*)(ag + (size_t)i * 32 * lda + k0); rb1[i] = *(const u32x4*)(bg + (size_t)i * 32 * ldb + k0); }
;     }
;     compute(1);
;     if (kt + 2 < KT) {
; #pragma unroll
;       for (int i = 0; i < 4; ++i) { *(u32x4*)(asw + 32 * i * 72) = ra0[i]; *(u32x4*)(bsw + 32 * i * 72) = rb0[i]; }
;     }
;     __syncthreads();
	global_load_dwordx4 v[148:151], v[80:81], off offset:512
	global_load_dwordx4 v[152:155], v[82:83], off offset:512
	global_load_dwordx4 v[156:159], v[84:85], off offset:512
	global_load_dwordx4 v[160:163], v[86:87], off offset:512
	global_load_dwordx4 v[164:167], v[88:89], off offset:512
	global_load_dwordx4 v[168:171], v[90:91], off offset:512
	global_load_dwordx4 v[172:175], v[92:93], off offset:512
	global_load_dwordx4 v[176:179], v[94:95], off offset:512
	ds_read_b128 v[180:183], v124 offset:16
	ds_read_b128 v[184:187], v124 offset:48
	ds_read_b128 v[190:193], v124 offset:4624
	ds_read_b128 v[194:197], v124 offset:4656
	ds_read_b128 v[198:201], v126 offset:36880
	ds_read_b128 v[202:205], v126 offset:36912
	ds_read_b128 v[206:209], v126 offset:41488
	ds_read_b128 v[210:213], v126 offset:41520
	s_waitcnt lgkmcnt(1)
	v_mfma_f32_32x32x16_bf16 v[2:17], v[206:209], v[190:193], v[2:17]
	v_mfma_f32_32x32x16_bf16 v[50:65], v[198:201], v[180:183], v[50:65]
	v_mfma_f32_32x32x16_bf16 v[34:49], v[206:209], v[180:183], v[34:49]
	v_mfma_f32_32x32x16_bf16 v[18:33], v[198:201], v[190:193], v[18:33]
	ds_read_b128 v[180:183], v124 offset:80
	ds_read_b128 v[190:193], v124 offset:4688
	ds_read_b128 v[198:201], v126 offset:36944
	ds_read_b128 v[206:209], v126 offset:41552
	s_waitcnt lgkmcnt(4)
	v_mfma_f32_32x32x16_bf16 v[2:17], v[210:213], v[194:197], v[2:17]
	v_mfma_f32_32x32x16_bf16 v[50:65], v[202:205], v[184:187], v[50:65]
	v_mfma_f32_32x32x16_bf16 v[34:49], v[210:213], v[184:187], v[34:49]
	v_mfma_f32_32x32x16_bf16 v[18:33], v[202:205], v[194:197], v[18:33]
	ds_read_b128 v[184:187], v124 offset:112
	ds_read_b128 v[194:197], v124 offset:4720
	ds_read_b128 v[202:205], v126 offset:36976
	ds_read_b128 v[210:213], v126 offset:41584
	s_waitcnt lgkmcnt(4)
	v_mfma_f32_32x32x16_bf16 v[2:17], v[206:209], v[190:193], v[2:17]
	v_mfma_f32_32x32x16_bf16 v[50:65], v[198:201], v[180:183], v[50:65]
	v_mfma_f32_32x32x16_bf16 v[34:49], v[206:209], v[180:183], v[34:49]
	v_mfma_f32_32x32x16_bf16 v[18:33], v[198:201], v[190:193], v[18:33]
	s_waitcnt lgkmcnt(0)
	v_mfma_f32_32x32x16_bf16 v[2:17], v[210:213], v[194:197], v[2:17]
	v_mfma_f32_32x32x16_bf16 v[50:65], v[202:205], v[184:187], v[50:65]
	v_mfma_f32_32x32x16_bf16 v[34:49], v[210:213], v[184:187], v[34:49]
	v_mfma_f32_32x32x16_bf16 v[18:33], v[202:205], v[194:197], v[18:33]
	s_waitcnt vmcnt(15)
	ds_write_b128 v121, v[96:99] offset:18448
	s_waitcnt vmcnt(14)
	ds_write_b128 v121, v[100:103] offset:55312
	s_waitcnt vmcnt(13)
	ds_write_b128 v121, v[104:107] offset:23056
	s_waitcnt vmcnt(12)
	ds_write_b128 v121, v[108:111] offset:59920
	s_waitcnt vmcnt(11)
	ds_write_b128 v121, v[112:115] offset:27664
	s_waitcnt vmcnt(10)
	ds_write_b128 v121, v[116:119] offset:64528
	s_waitcnt vmcnt(9)
	ds_write_b128 v121, v[140:143] offset:32272
	s_waitcnt vmcnt(8)
	ds_write_b128 v122, v[144:147] offset:32256
	s_waitcnt lgkmcnt(0)
	s_barrier
	global_load_dwordx4 v[96:99], v[80:81], off offset:640
	global_load_dwordx4 v[100:103], v[82:83], off offset:640
	global_load_dwordx4 v[104:107], v[84:85], off offset:640
	global_load_dwordx4 v[108:111], v[86:87], off offset:640
	global_load_dwordx4 v[112:115], v[88:89], off offset:640
	global_load_dwordx4 v[116:119], v[90:91], off offset:640
	global_load_dwordx4 v[140:143], v[92:93], off offset:640
	global_load_dwordx4 v[144:147], v[94:95], off offset:640
	ds_read_b128 v[180:183], v124 offset:18448
	ds_read_b128 v[184:187], v124 offset:18480
	ds_read_b128 v[190:193], v124 offset:23056
	ds_read_b128 v[194:197], v124 offset:23088
	ds_read_b128 v[198:201], v126 offset:55312
	ds_read_b128 v[202:205], v126 offset:55344
	ds_read_b128 v[206:209], v126 offset:59920
	ds_read_b128 v[210:213], v126 offset:59952
	s_waitcnt lgkmcnt(1)
	v_mfma_f32_32x32x16_bf16 v[2:17], v[206:209], v[190:193], v[2:17]
	v_mfma_f32_32x32x16_bf16 v[50:65], v[198:201], v[180:183], v[50:65]
	v_mfma_f32_32x32x16_bf16 v[34:49], v[206:209], v[180:183], v[34:49]
	v_mfma_f32_32x32x16_bf16 v[18:33], v[198:201], v[190:193], v[18:33]
	ds_read_b128 v[180:183], v124 offset:18512
	ds_read_b128 v[190:193], v124 offset:23120
	ds_read_b128 v[198:201], v126 offset:55376
	ds_read_b128 v[206:209], v126 offset:59984
	s_waitcnt lgkmcnt(4)
	v_mfma_f32_32x32x16_bf16 v[2:17], v[210:213], v[194:197], v[2:17]
	v_mfma_f32_32x32x16_bf16 v[50:65], v[202:205], v[184:187], v[50:65]
	v_mfma_f32_32x32x16_bf16 v[34:49], v[210:213], v[184:187], v[34:49]
	v_mfma_f32_32x32x16_bf16 v[18:33], v[202:205], v[194:197], v[18:33]
	ds_read_b128 v[184:187], v124 offset:18544
	ds_read_b128 v[194:197], v124 offset:23152
	ds_read_b128 v[202:205], v126 offset:55408
	ds_read_b128 v[210:213], v126 offset:60016
	s_waitcnt lgkmcnt(4)
	v_mfma_f32_32x32x16_bf16 v[2:17], v[206:209], v[190:193], v[2:17]
	v_mfma_f32_32x32x16_bf16 v[50:65], v[198:201], v[180:183], v[50:65]
	v_mfma_f32_32x32x16_bf16 v[34:49], v[206:209], v[180:183], v[34:49]
	v_mfma_f32_32x32x16_bf16 v[18:33], v[198:201], v[190:193], v[18:33]
	s_waitcnt lgkmcnt(0)
	v_mfma_f32_32x32x16_bf16 v[2:17], v[210:213], v[194:197], v[2:17]
	v_mfma_f32_32x32x16_bf16 v[50:65], v[202:205], v[184:187], v[50:65]
	v_mfma_f32_32x32x16_bf16 v[34:49], v[210:213], v[184:187], v[34:49]
	v_mfma_f32_32x32x16_bf16 v[18:33], v[202:205], v[194:197], v[18:33]
	s_waitcnt vmcnt(15)
	ds_write_b128 v121, v[148:151] offset:16
	s_waitcnt vmcnt(14)
	ds_write_b128 v121, v[152:155] offset:36880
	s_waitcnt vmcnt(13)
	ds_write_b128 v121, v[156:159] offset:4624
	s_waitcnt vmcnt(12)
	ds_write_b128 v121, v[160:163] offset:41488
	s_waitcnt vmcnt(11)
	ds_write_b128 v121, v[164:167] offset:9232
	s_waitcnt vmcnt(10)
	ds_write_b128 v121, v[168:171] offset:46096
	s_waitcnt vmcnt(9)
	ds_write_b128 v121, v[172:175] offset:13840
	s_waitcnt vmcnt(8)
	ds_write_b128 v121, v[176:179] offset:50704
	s_waitcnt lgkmcnt(0)
	s_barrier
; template <bool SWAP, class Epi>
; DI void gemm_tile(const u16* __restrict__ A, int lda, const u16* __restrict__ Bt, int ldb, int K, int m0, int n0, char* smem, Epi&& epi) {
;     ...
;   for (int kt = 0; kt < KT; kt += 2) {
;     if (kt + 2 < KT) {
;       const int k0 = (kt + 2) << 6;
; #pragma unroll
;       for (int i = 0; i < 4; ++i) { ra0[i] = *(const u32x4*)(ag + (size_t)i * 32 * lda + k0); rb0[i] = *(const u32x4*)(bg + (size_t)i * 32 * ldb + k0); }
;     }
;     compute(0);
; #pragma unroll
;     for (int i = 0; i < 4; ++i) { *(u32x4*)(asw + 128 * 72 + 32 * i * 72) = ra1[i]; *(u32x4*)(bsw + 128 * 72 + 32 * i * 72) = rb1[i]; }
;     __syncthreads();
;     if (kt + 3 < KT) {
;       const int k0 = (kt + 3) << 6;
; #pragma unroll
;       for (int i = 0; i < 4; ++i) { ra1[i] = *(const u32x4*)(ag + (size_t)i * 32 * lda + k0); rb1[i] = *(const u32x4*)(bg + (size_t)i * 32 * ldb + k0); }
;     }
;     compute(1);
;     if (kt + 2 < KT) {
; #pragma unroll
;       for (int i = 0; i < 4; ++i) { *(u32x4*)(asw + 32 * i * 72) = ra0[i]; *(u32x4*)(bsw + 32 * i * 72) = rb0[i]; }
;     }
;     __syncthreads();
	global_load_dwordx4 v[148:151], v[80:81], off offset:768
	global_load_dwordx4 v[152:155], v[82:83], off offset:768
	global_load_dwordx4 v[156:159], v[84:85], off offset:768
	global_load_dwordx4 v[160:163], v[86:87], off offset:768
	global_load_dwordx4 v[164:167], v[88:89], off offset:768
	global_load_dwordx4 v[168:171], v[90:91], off offset:768
	global_load_dwordx4 v[172:175], v[92:93], off offset:768
	global_load_dwordx4 v[176:179], v[94:95], off offset:768
	ds_read_b128 v[180:183], v124 offset:16
	ds_read_b128 v[184:187], v124 offset:48
	ds_read_b128 v[190:193], v124 offset:4624
	ds_read_b128 v[194:197], v124 offset:4656
	ds_read_b128 v[198:201], v126 offset:36880
	ds_read_b128 v[202:205], v126 offset:36912
	ds_read_b128 v[206:209], v126 offset:41488
	ds_read_b128 v[210:213], v126 offset:41520
	s_waitcnt lgkmcnt(1)
	v_mfma_f32_32x32x16_bf16 v[2:17], v[206:209], v[190:193], v[2:17]
	v_mfma_f32_32x32x16_bf16 v[50:65], v[198:201], v[180:183], v[50:65]
	v_mfma_f32_32x32x16_bf16 v[34:49], v[206:209], v[180:183], v[34:49]
	v_mfma_f32_32x32x16_bf16 v[18:33], v[198:201], v[190:193], v[18:33]
	ds_read_b128 v[180:183], v124 offset:80
	ds_read_b128 v[190:193], v124 offset:4688
	ds_read_b128 v[198:201], v126 offset:36944
	ds_read_b128 v[206:209], v126 offset:41552
	s_waitcnt lgkmcnt(4)
	v_mfma_f32_32x32x16_bf16 v[2:17], v[210:213], v[194:197], v[2:17]
	v_mfma_f32_32x32x16_bf16 v[50:65], v[202:205], v[184:187], v[50:65]
	v_mfma_f32_32x32x16_bf16 v[34:49], v[210:213], v[184:187], v[34:49]
	v_mfma_f32_32x32x16_bf16 v[18:33], v[202:205], v[194:197], v[18:33]
	ds_read_b128 v[184:187], v124 offset:112
	ds_read_b128 v[194:197], v124 offset:4720
	ds_read_b128 v[202:205], v126 offset:36976
	ds_read_b128 v[210:213], v126 offset:41584
	s_waitcnt lgkmcnt(4)
	v_mfma_f32_32x32x16_bf16 v[2:17], v[206:209], v[190:193], v[2:17]
	v_mfma_f32_32x32x16_bf16 v[50:65], v[198:201], v[180:183], v[50:65]
	v_mfma_f32_32x32x16_bf16 v[34:49], v[206:209], v[180:183], v[34:49]
	v_mfma_f32_32x32x16_bf16 v[18:33], v[198:201], v[190:193], v[18:33]
	s_waitcnt lgkmcnt(0)
	v_mfma_f32_32x32x16_bf16 v[2:17], v[210:213], v[194:197], v[2:17]
	v_mfma_f32_32x32x16_bf16 v[50:65], v[202:205], v[184:187], v[50:65]
	v_mfma_f32_32x32x16_bf16 v[34:49], v[210:213], v[184:187], v[34:49]
	v_mfma_f32_32x32x16_bf16 v[18:33], v[202:205], v[194:197], v[18:33]
	s_waitcnt vmcnt(15)
	ds_write_b128 v121, v[96:99] offset:18448
	s_waitcnt vmcnt(14)
	ds_write_b128 v121, v[100:103] offset:55312
	s_waitcnt vmcnt(13)
	ds_write_b128 v121, v[104:107] offset:23056
	s_waitcnt vmcnt(12)
	ds_write_b128 v121, v[108:111] offset:59920
	s_waitcnt vmcnt(11)
	ds_write_b128 v121, v[112:115] offset:27664
	s_waitcnt vmcnt(10)
	ds_write_b128 v121, v[116:119] offset:64528
	s_waitcnt vmcnt(9)
	ds_write_b128 v121, v[140:143] offset:32272
	s_waitcnt vmcnt(8)
	ds_write_b128 v122, v[144:147] offset:32256
	s_waitcnt lgkmcnt(0)
	s_barrier
	global_load_dwordx4 v[96:99], v[80:81], off offset:896
	s_nop 0
	global_load_dwordx4 v[80:83], v[82:83], off offset:896
	s_nop 0
	global_load_dwordx4 v[100:103], v[84:85], off offset:896
	s_nop 0
	global_load_dwordx4 v[84:87], v[86:87], off offset:896
	s_nop 0
	global_load_dwordx4 v[104:107], v[88:89], off offset:896
	s_nop 0
	global_load_dwordx4 v[88:91], v[90:91], off offset:896
	s_nop 0
	global_load_dwordx4 v[108:111], v[92:93], off offset:896
	s_nop 0
	global_load_dwordx4 v[92:95], v[94:95], off offset:896
	ds_read_b128 v[112:115], v124 offset:18448
	ds_read_b128 v[116:119], v124 offset:18480
	ds_read_b128 v[140:143], v124 offset:23056
	ds_read_b128 v[144:147], v124 offset:23088
	ds_read_b128 v[180:183], v126 offset:55312
	ds_read_b128 v[184:187], v126 offset:55344
	ds_read_b128 v[190:193], v126 offset:59920
	ds_read_b128 v[194:197], v126 offset:59952
	s_waitcnt lgkmcnt(1)
	v_mfma_f32_32x32x16_bf16 v[2:17], v[190:193], v[140:143], v[2:17]
	v_mfma_f32_32x32x16_bf16 v[50:65], v[180:183], v[112:115], v[50:65]
	v_mfma_f32_32x32x16_bf16 v[34:49], v[190:193], v[112:115], v[34:49]
	v_mfma_f32_32x32x16_bf16 v[18:33], v[180:183], v[140:143], v[18:33]
	ds_read_b128 v[112:115], v124 offset:18512
	ds_read_b128 v[140:143], v124 offset:23120
	ds_read_b128 v[180:183], v126 offset:55376
	ds_read_b128 v[190:193], v126 offset:59984
	s_waitcnt lgkmcnt(4)
	v_mfma_f32_32x32x16_bf16 v[2:17], v[194:197], v[144:147], v[2:17]
	v_mfma_f32_32x32x16_bf16 v[50:65], v[184:187], v[116:119], v[50:65]
	v_mfma_f32_32x32x16_bf16 v[34:49], v[194:197], v[116:119], v[34:49]
	v_mfma_f32_32x32x16_bf16 v[18:33], v[184:187], v[144:147], v[18:33]
	ds_read_b128 v[116:119], v124 offset:18544
	ds_read_b128 v[144:147], v124 offset:23152
	ds_read_b128 v[184:187], v126 offset:55408
	ds_read_b128 v[194:197], v126 offset:60016
	s_waitcnt lgkmcnt(4)
	v_mfma_f32_32x32x16_bf16 v[2:17], v[190:193], v[140:143], v[2:17]
	v_mfma_f32_32x32x16_bf16 v[50:65], v[180:183], v[112:115], v[50:65]
	v_mfma_f32_32x32x16_bf16 v[34:49], v[190:193], v[112:115], v[34:49]
	v_mfma_f32_32x32x16_bf16 v[18:33], v[180:183], v[140:143], v[18:33]
	s_waitcnt lgkmcnt(0)
	v_mfma_f32_32x32x16_bf16 v[2:17], v[194:197], v[144:147], v[2:17]
	v_mfma_f32_32x32x16_bf16 v[50:65], v[184:187], v[116:119], v[50:65]
	v_mfma_f32_32x32x16_bf16 v[34:49], v[194:197], v[116:119], v[34:49]
	v_mfma_f32_32x32x16_bf16 v[18:33], v[184:187], v[144:147], v[18:33]
	s_waitcnt vmcnt(15)
	ds_write_b128 v121, v[148:151] offset:16
	s_waitcnt vmcnt(14)
	ds_write_b128 v121, v[152:155] offset:36880
	s_waitcnt vmcnt(13)
	ds_write_b128 v121, v[156:159] offset:4624
	s_waitcnt vmcnt(12)
	ds_write_b128 v121, v[160:163] offset:41488
	s_waitcnt vmcnt(11)
	ds_write_b128 v121, v[164:167] offset:9232
	s_waitcnt vmcnt(10)
	ds_write_b128 v121, v[168:171] offset:46096
	s_waitcnt vmcnt(9)
	ds_write_b128 v121, v[172:175] offset:13840
	s_waitcnt vmcnt(8)
	ds_write_b128 v121, v[176:179] offset:50704
	s_waitcnt lgkmcnt(0)
	s_barrier
; template <bool SWAP, class Epi>
; DI void gemm_tile(const u16* __restrict__ A, int lda, const u16* __restrict__ Bt, int ldb, int K, int m0, int n0, char* smem, Epi&& epi) {
;     ...
;   for (int kt = 0; kt < KT; kt += 2) {
;     if (kt + 2 < KT) {
;       const int k0 = (kt + 2) << 6;
; #pragma unroll
;       for (int i = 0; i < 4; ++i) { ra0[i] = *(const u32x4*)(ag + (size_t)i * 32 * lda + k0); rb0[i] = *(const u32x4*)(bg + (size_t)i * 32 * ldb + k0); }
;     }
;     compute(0);
; #pragma unroll
;     for (int i = 0; i < 4; ++i) { *(u32x4*)(asw + 128 * 72 + 32 * i * 72) = ra1[i]; *(u32x4*)(bsw + 128 * 72 + 32 * i * 72) = rb1[i]; }
;     __syncthreads();
;     if (kt + 3 < KT) {
;       const int k0 = (kt + 3) << 6;
; #pragma unroll
;       for (int i = 0; i < 4; ++i) { ra1[i] = *(const u32x4*)(ag + (size_t)i * 32 * lda + k0); rb1[i] = *(const u32x4*)(bg + (size_t)i * 32 * ldb + k0); }
;     }
;     compute(1);
;     if (kt + 2 < KT) {
; #pragma unroll
;       for (int i = 0; i < 4; ++i) { *(u32x4*)(asw + 32 * i * 72) = ra0[i]; *(u32x4*)(bsw + 32 * i * 72) = rb0[i]; }
;     }
;     __syncthreads();
	ds_read_b128 v[112:115], v124 offset:16
	ds_read_b128 v[116:119], v124 offset:48
	ds_read_b128 v[140:143], v124 offset:4624
	ds_read_b128 v[144:147], v124 offset:4656
	ds_read_b128 v[148:151], v126 offset:36880
	ds_read_b128 v[152:155], v126 offset:36912
	ds_read_b128 v[156:159], v126 offset:41488
	ds_read_b128 v[160:163], v126 offset:41520
	s_waitcnt lgkmcnt(1)
	v_mfma_f32_32x32x16_bf16 v[2:17], v[156:159], v[140:143], v[2:17]
	v_mfma_f32_32x32x16_bf16 v[50:65], v[148:151], v[112:115], v[50:65]
	v_mfma_f32_32x32x16_bf16 v[34:49], v[156:159], v[112:115], v[34:49]
	v_mfma_f32_32x32x16_bf16 v[18:33], v[148:151], v[140:143], v[18:33]
	ds_read_b128 v[112:115], v124 offset:80
	ds_read_b128 v[140:143], v124 offset:4688
	ds_read_b128 v[148:151], v126 offset:36944
	ds_read_b128 v[156:159], v126 offset:41552
	s_waitcnt lgkmcnt(4)
	v_mfma_f32_32x32x16_bf16 v[2:17], v[160:163], v[144:147], v[2:17]
	v_mfma_f32_32x32x16_bf16 v[50:65], v[152:155], v[116:119], v[50:65]
	v_mfma_f32_32x32x16_bf16 v[34:49], v[160:163], v[116:119], v[34:49]
	v_mfma_f32_32x32x16_bf16 v[18:33], v[152:155], v[144:147], v[18:33]
	ds_read_b128 v[116:119], v124 offset:112
	ds_read_b128 v[144:147], v124 offset:4720
	ds_read_b128 v[152:155], v126 offset:36976
	ds_read_b128 v[160:163], v126 offset:41584
	s_waitcnt lgkmcnt(4)
	v_mfma_f32_32x32x16_bf16 v[2:17], v[156:159], v[140:143], v[2:17]
	v_mfma_f32_32x32x16_bf16 v[50:65], v[148:151], v[112:115], v[50:65]
	v_mfma_f32_32x32x16_bf16 v[34:49], v[156:159], v[112:115], v[34:49]
	v_mfma_f32_32x32x16_bf16 v[18:33], v[148:151], v[140:143], v[18:33]
	s_waitcnt lgkmcnt(0)
	v_mfma_f32_32x32x16_bf16 v[2:17], v[160:163], v[144:147], v[2:17]
	v_mfma_f32_32x32x16_bf16 v[50:65], v[152:155], v[116:119], v[50:65]
	v_mfma_f32_32x32x16_bf16 v[34:49], v[160:163], v[116:119], v[34:49]
	v_mfma_f32_32x32x16_bf16 v[18:33], v[152:155], v[144:147], v[18:33]
	s_waitcnt vmcnt(7)
	ds_write_b128 v121, v[96:99] offset:18448
	s_waitcnt vmcnt(6)
	ds_write_b128 v121, v[80:83] offset:55312
	s_waitcnt vmcnt(5)
	ds_write_b128 v121, v[100:103] offset:23056
	s_waitcnt vmcnt(4)
	ds_write_b128 v121, v[84:87] offset:59920
	s_waitcnt vmcnt(3)
	ds_write_b128 v121, v[104:107] offset:27664
	s_waitcnt vmcnt(2)
	ds_write_b128 v121, v[88:91] offset:64528
	s_waitcnt vmcnt(1)
	ds_write_b128 v121, v[108:111] offset:32272
	s_waitcnt vmcnt(0)
	ds_write_b128 v122, v[92:95] offset:32256
	s_waitcnt lgkmcnt(0)
	s_barrier
	ds_read_b128 v[80:83], v124 offset:18448
	ds_read_b128 v[84:87], v124 offset:18480
	ds_read_b128 v[88:91], v124 offset:23056
	ds_read_b128 v[92:95], v124 offset:23088
	ds_read_b128 v[96:99], v126 offset:55312
	ds_read_b128 v[100:103], v126 offset:55344
	ds_read_b128 v[104:107], v126 offset:59920
	ds_read_b128 v[108:111], v126 offset:59952
	s_waitcnt lgkmcnt(1)
	v_mfma_f32_32x32x16_bf16 v[2:17], v[104:107], v[88:91], v[2:17]
	v_mfma_f32_32x32x16_bf16 v[50:65], v[96:99], v[80:83], v[50:65]
	v_mfma_f32_32x32x16_bf16 v[34:49], v[104:107], v[80:83], v[34:49]
	v_mfma_f32_32x32x16_bf16 v[18:33], v[96:99], v[88:91], v[18:33]
	ds_read_b128 v[80:83], v124 offset:18512
	ds_read_b128 v[88:91], v124 offset:23120
	ds_read_b128 v[96:99], v126 offset:55376
	ds_read_b128 v[104:107], v126 offset:59984
	s_waitcnt lgkmcnt(4)
	v_mfma_f32_32x32x16_bf16 v[2:17], v[108:111], v[92:95], v[2:17]
	v_mfma_f32_32x32x16_bf16 v[50:65], v[100:103], v[84:87], v[50:65]
	v_mfma_f32_32x32x16_bf16 v[34:49], v[108:111], v[84:87], v[34:49]
	v_mfma_f32_32x32x16_bf16 v[18:33], v[100:103], v[92:95], v[18:33]
	ds_read_b128 v[84:87], v124 offset:18544
	ds_read_b128 v[92:95], v124 offset:23152
	ds_read_b128 v[100:103], v126 offset:55408
	ds_read_b128 v[108:111], v126 offset:60016
	s_waitcnt lgkmcnt(4)
	v_mfma_f32_32x32x16_bf16 v[2:17], v[104:107], v[88:91], v[2:17]
	v_mfma_f32_32x32x16_bf16 v[50:65], v[96:99], v[80:83], v[50:65]
	v_mfma_f32_32x32x16_bf16 v[34:49], v[104:107], v[80:83], v[34:49]
	v_mfma_f32_32x32x16_bf16 v[18:33], v[96:99], v[88:91], v[18:33]
	s_waitcnt lgkmcnt(0)
	v_mfma_f32_32x32x16_bf16 v[2:17], v[108:111], v[92:95], v[2:17]
	v_mfma_f32_32x32x16_bf16 v[50:65], v[100:103], v[84:87], v[50:65]
	v_mfma_f32_32x32x16_bf16 v[34:49], v[108:111], v[84:87], v[34:49]
	v_mfma_f32_32x32x16_bf16 v[18:33], v[100:103], v[92:95], v[18:33]
	s_barrier
; DI unsigned pk2(float a, float b) { f2_t v = {a, b}; bf2_t r = __builtin_convertvector(v, bf2_t); return __builtin_bit_cast(unsigned, r); }
; DI void phase3(const Params& p, char* smem) {
;     ...
;         gemm_tile<true>(P + 3584, INC, (const u16*)(p.ws + WS_WUKVT), 512, 512, tm * 128, tn * 128, smem, [&](f32x16 (&acc)[2][2], int mb, int nb, int r, int hi) __attribute__((always_inline)) {
; #pragma unroll
;           for (int mi = 0; mi < 2; ++mi) {
;             const int row = mb + mi * 32 + r;
;             const float sc = rs[row - tm * 128];
; #pragma unroll
;             for (int ni = 0; ni < 2; ++ni)
; #pragma unroll
;               for (int g = 0; g < 4; ++g) {
;                 const int d = (nb & 127) + ni * 32 + hi * 4 + 8 * g;
;                 *(uint2*)(Kb + (size_t)row * 1536 + head * 192 + d) = make_uint2(pk2(acc[mi][ni][4 * g] * sc, acc[mi][ni][4 * g + 1] * sc), pk2(acc[mi][ni][4 * g + 2] * sc, acc[mi][ni][4 * g + 3] * sc));
;               }
;           }
;         });
	v_add_u32_e32 v79, s92, v123
	ds_read_b32 v80, v130
	v_mul_u32_u24_e32 v66, 0xc00, v79
	v_or_b32_e32 v79, 32, v79
	v_subrev_u32_e32 v79, s92, v79
	v_lshl_add_u32 v79, v79, 2, 0
	v_add_u32_e32 v79, 0x12010, v79
	ds_read_b32 v82, v79
	s_waitcnt lgkmcnt(1)
	v_pk_mul_f32 v[50:51], v[50:51], v[80:81] op_sel_hi:[1,0]
	v_pk_mul_f32 v[52:53], v[52:53], v[80:81] op_sel_hi:[1,0]
	v_cvt_pk_bf16_f32 v50, v50, v51
	v_cvt_pk_bf16_f32 v51, v52, v53
	v_lshl_add_u64 v[52:53], s[4:5], 0, v[66:67]
	s_mulk_i32 s16, 0xc0
	v_lshl_add_u64 v[52:53], s[16:17], 1, v[52:53]
	v_mov_b32_e32 v79, v67
	v_pk_mul_f32 v[34:35], v[34:35], v[80:81] op_sel_hi:[1,0]
	v_pk_mul_f32 v[36:37], v[36:37], v[80:81] op_sel_hi:[1,0]
	v_lshl_add_u64 v[52:53], v[52:53], 0, v[78:79]
	v_cvt_pk_bf16_f32 v34, v34, v35
	v_cvt_pk_bf16_f32 v35, v36, v37
	global_store_dwordx2 v[52:53], v[34:35], off offset:64
	v_pk_mul_f32 v[34:35], v[38:39], v[80:81] op_sel_hi:[1,0]
	v_pk_mul_f32 v[36:37], v[40:41], v[80:81] op_sel_hi:[1,0]
	v_cvt_pk_bf16_f32 v34, v34, v35
	v_cvt_pk_bf16_f32 v35, v36, v37
	global_store_dwordx2 v[52:53], v[34:35], off offset:80
	v_pk_mul_f32 v[34:35], v[42:43], v[80:81] op_sel_hi:[1,0]
	v_pk_mul_f32 v[36:37], v[44:45], v[80:81] op_sel_hi:[1,0]
	v_cvt_pk_bf16_f32 v34, v34, v35
	v_cvt_pk_bf16_f32 v35, v36, v37
	global_store_dwordx2 v[52:53], v[34:35], off offset:96
	v_pk_mul_f32 v[34:35], v[46:47], v[80:81] op_sel_hi:[1,0]
	v_pk_mul_f32 v[36:37], v[48:49], v[80:81] op_sel_hi:[1,0]
	v_cvt_pk_bf16_f32 v34, v34, v35
	v_cvt_pk_bf16_f32 v35, v36, v37
	global_store_dwordx2 v[52:53], v[34:35], off offset:112
	s_waitcnt lgkmcnt(0)
	v_pk_mul_f32 v[18:19], v[18:19], v[82:83] op_sel_hi:[1,0]
	v_pk_mul_f32 v[20:21], v[20:21], v[82:83] op_sel_hi:[1,0]
	v_add_co_u32_e32 v34, vcc, s62, v52
	v_pk_mul_f32 v[2:3], v[2:3], v[82:83] op_sel_hi:[1,0]
	v_pk_mul_f32 v[4:5], v[4:5], v[82:83] op_sel_hi:[1,0]
	v_cvt_pk_bf16_f32 v18, v18, v19
	v_cvt_pk_bf16_f32 v19, v20, v21
	v_lshl_add_u64 v[20:21], v[52:53], 0, s[30:31]
	v_addc_co_u32_e32 v35, vcc, 0, v53, vcc
	v_cvt_pk_bf16_f32 v2, v2, v3
	v_cvt_pk_bf16_f32 v3, v4, v5
	global_store_dwordx2 v[52:53], v[50:51], off
	v_pk_mul_f32 v[50:51], v[54:55], v[80:81] op_sel_hi:[1,0]
	v_pk_mul_f32 v[54:55], v[56:57], v[80:81] op_sel_hi:[1,0]
	global_store_dwordx2 v[34:35], v[18:19], off
	v_pk_mul_f32 v[18:19], v[22:23], v[82:83] op_sel_hi:[1,0]
	v_pk_mul_f32 v[22:23], v[24:25], v[82:83] op_sel_hi:[1,0]
	global_store_dwordx2 v[20:21], v[2:3], off offset:64
	v_pk_mul_f32 v[2:3], v[6:7], v[82:83] op_sel_hi:[1,0]
	v_pk_mul_f32 v[4:5], v[8:9], v[82:83] op_sel_hi:[1,0]
	v_cvt_pk_bf16_f32 v50, v50, v51
	v_cvt_pk_bf16_f32 v51, v54, v55
	v_cvt_pk_bf16_f32 v18, v18, v19
	v_cvt_pk_bf16_f32 v19, v22, v23
	v_cvt_pk_bf16_f32 v2, v2, v3
	v_cvt_pk_bf16_f32 v3, v4, v5
	global_store_dwordx2 v[52:53], v[50:51], off offset:16
	v_pk_mul_f32 v[50:51], v[58:59], v[80:81] op_sel_hi:[1,0]
	v_pk_mul_f32 v[54:55], v[60:61], v[80:81] op_sel_hi:[1,0]
	global_store_dwordx2 v[20:21], v[18:19], off offset:16
	v_pk_mul_f32 v[18:19], v[26:27], v[82:83] op_sel_hi:[1,0]
	v_pk_mul_f32 v[22:23], v[28:29], v[82:83] op_sel_hi:[1,0]
	global_store_dwordx2 v[20:21], v[2:3], off offset:80
	v_pk_mul_f32 v[2:3], v[10:11], v[82:83] op_sel_hi:[1,0]
	v_pk_mul_f32 v[4:5], v[12:13], v[82:83] op_sel_hi:[1,0]
	v_cvt_pk_bf16_f32 v50, v50, v51
	v_cvt_pk_bf16_f32 v51, v54, v55
	v_cvt_pk_bf16_f32 v18, v18, v19
	v_cvt_pk_bf16_f32 v19, v22, v23
	v_cvt_pk_bf16_f32 v2, v2, v3
	v_cvt_pk_bf16_f32 v3, v4, v5
	global_store_dwordx2 v[52:53], v[50:51], off offset:32
	v_pk_mul_f32 v[50:51], v[62:63], v[80:81] op_sel_hi:[1,0]
	v_pk_mul_f32 v[54:55], v[64:65], v[80:81] op_sel_hi:[1,0]
	global_store_dwordx2 v[20:21], v[18:19], off offset:32
	v_pk_mul_f32 v[18:19], v[30:31], v[82:83] op_sel_hi:[1,0]
	v_pk_mul_f32 v[22:23], v[32:33], v[82:83] op_sel_hi:[1,0]
	global_store_dwordx2 v[20:21], v[2:3], off offset:96
	v_pk_mul_f32 v[2:3], v[14:15], v[82:83] op_sel_hi:[1,0]
	v_pk_mul_f32 v[4:5], v[16:17], v[82:83] op_sel_hi:[1,0]
	v_cvt_pk_bf16_f32 v50, v50, v51
	v_cvt_pk_bf16_f32 v51, v54, v55
	v_cvt_pk_bf16_f32 v18, v18, v19
	v_cvt_pk_bf16_f32 v19, v22, v23
	v_cvt_pk_bf16_f32 v2, v2, v3
	v_lshl_add_u64 v[8:9], v[20:21], 0, s[48:49]
	v_mov_b32_e32 v6, v5
	global_store_dwordx2 v[52:53], v[50:51], off offset:48
	global_store_dwordx2 v[20:21], v[18:19], off offset:48
	global_store_dword v[20:21], v2, off offset:112

; template <bool SWAP, class Epi>
; DI void gemm_tile(const u16* __restrict__ A, int lda, const u16* __restrict__ Bt, int ldb, int K, int m0, int n0, char* smem, Epi&& epi) {
;     ...
;   const int srow = tid >> 3, skc = tid & 7;
;   const u16* ag = A + (size_t)(m0 + srow) * lda + skc * 8;
;   const u16* bg = Bt + (size_t)(n0 + srow) * ldb + skc * 8;
;   u16* asw = As + srow * 72 + skc * 8;
;   u16* bsw = Bs + srow * 72 + skc * 8;
;   u32x4 ra0[4], rb0[4], ra1[4], rb1[4];
; #pragma unroll
;   for (int i = 0; i < 4; ++i) { ra0[i] = *(const u32x4*)(ag + (size_t)i * 32 * lda); rb0[i] = *(const u32x4*)(bg + (size_t)i * 32 * ldb); }
; #pragma unroll
;   for (int i = 0; i < 4; ++i) { ra1[i] = *(const u32x4*)(ag + (size_t)i * 32 * lda + 64); rb1[i] = *(const u32x4*)(bg + (size_t)i * 32 * ldb + 64); }
;   __syncthreads();
; #pragma unroll
;   for (int i = 0; i < 4; ++i) { *(u32x4*)(asw + 32 * i * 72) = ra0[i]; *(u32x4*)(bsw + 32 * i * 72) = rb0[i]; }
;   __syncthreads();
; DI void phase3(const Params& p, char* smem) {
;     ...
;       const int tn = it / 64, tm = it % 64;
;       __syncthreads();
;       if (threadIdx.x < 128) { const float4* sp = (const float4*)(SSQ + (size_t)(tm * 128 + threadIdx.x) * 16); const float4 a = sp[0], b = sp[1]; rs[threadIdx.x] = rsqrtf((((a.x + a.y) + (a.z + a.w)) + ((b.x + b.y) + (b.z + b.w))) * (1.f / 512.f) + EPS); }
;       gemm_tile<true>(P + 3072, INC, (const u16*)(p.ws + WS_WUQT), 512, 512, tm * 128, tn * 128, smem, [&](f32x16 (&acc)[2][2], int mb, int nb, int r, int hi) __attribute__((always_inline)) {
.LBB0_516:
	s_and_b64 vcc, exec, s[50:51]
	s_cbranch_vccz .LBB0_507
	s_ashr_i32 s16, s13, 31
	s_lshr_b32 s16, s16, 26
	s_add_i32 s16, s13, s16
	s_ashr_i32 s16, s16, 6
	s_barrier
	s_waitcnt lgkmcnt(0)
	s_and_saveexec_b64 s[50:51], s[2:3]
	s_cbranch_execz .LBB0_519
	s_lshl_b32 s92, s16, 13
	s_sub_i32 s92, 0, s92
	s_add_i32 s92, s92, s59
	v_add_u32_e32 v66, s92, v0
	v_lshlrev_b64 v[238:239], 6, v[66:67]
	v_lshl_add_u64 v[242:243], s[14:15], 0, v[238:239]
	global_load_dwordx4 v[238:241], v[242:243], off
	s_nop 0
	global_load_dwordx4 v[242:245], v[242:243], off offset:16
.LBB0_519:
	s_or_b64 exec, exec, s[50:51]
	s_mul_i32 s51, s16, 0xfbf00000
	v_add_u32_e32 v2, s51, v135
	s_lshl_b32 s50, s16, 7
	v_ashrrev_i32_e32 v3, 31, v2
	v_lshl_add_u64 v[80:81], v[72:73], 0, v[2:3]
	v_or_b32_e32 v2, s50, v120
	v_ashrrev_i32_e32 v3, 31, v2
	v_lshlrev_b64 v[2:3], 10, v[2:3]
	v_add_co_u32_e32 v84, vcc, 0x41000, v80
	v_lshl_add_u64 v[82:83], v[76:77], 0, v[2:3]
	s_nop 0
	v_addc_co_u32_e32 v85, vcc, 0, v81, vcc
	v_add_co_u32_e32 v86, vcc, 0x8000, v82
	global_load_dwordx4 v[2:5], v[80:81], off
	global_load_dwordx4 v[6:9], v[82:83], off
	v_addc_co_u32_e32 v87, vcc, 0, v83, vcc
	v_add_co_u32_e32 v88, vcc, 0x82000, v80
	global_load_dwordx4 v[10:13], v[84:85], off
	global_load_dwordx4 v[14:17], v[86:87], off
	v_addc_co_u32_e32 v89, vcc, 0, v81, vcc
	v_add_co_u32_e32 v90, vcc, 0x10000, v82
	global_load_dwordx4 v[18:21], v[88:89], off
	s_nop 0
	v_addc_co_u32_e32 v91, vcc, 0, v83, vcc
	v_add_co_u32_e32 v92, vcc, 0xc3000, v80
	global_load_dwordx4 v[22:25], v[90:91], off
	s_nop 0
	v_addc_co_u32_e32 v93, vcc, 0, v81, vcc
	global_load_dwordx4 v[26:29], v[92:93], off
	v_add_co_u32_e32 v94, vcc, s62, v82
	s_nop 1
	v_addc_co_u32_e32 v95, vcc, 0, v83, vcc
	global_load_dwordx4 v[30:33], v[94:95], off
	global_load_dwordx4 v[96:99], v[80:81], off offset:128
	global_load_dwordx4 v[100:103], v[82:83], off offset:128
	global_load_dwordx4 v[104:107], v[84:85], off offset:128
	global_load_dwordx4 v[108:111], v[86:87], off offset:128
	global_load_dwordx4 v[112:115], v[88:89], off offset:128
	global_load_dwordx4 v[116:119], v[90:91], off offset:128
	global_load_dwordx4 v[140:143], v[92:93], off offset:128
	global_load_dwordx4 v[144:147], v[94:95], off offset:128
	s_and_saveexec_b64 s[96:97], s[2:3]
	s_cbranch_execz .Lp3_rsQ
	s_waitcnt vmcnt(16)
	v_add_f32_e32 v238, v238, v239
	v_add_f32_e32 v240, v240, v241
	v_add_f32_e32 v242, v242, v243
	v_add_f32_e32 v244, v244, v245
	v_add_f32_e32 v238, v238, v240
	v_add_f32_e32 v242, v242, v244
	v_add_f32_e32 v238, v238, v242
	v_fmamk_f32 v238, v238, 0x3b000000, v138
	v_mul_f32_e32 v239, 0x4b800000, v238
	v_cmp_gt_f32_e32 vcc, s66, v238
	s_nop 1
	v_cndmask_b32_e32 v238, v238, v239, vcc
	v_rsq_f32_e32 v238, v238
	s_nop 0
	v_mul_f32_e32 v239, 0x45800000, v238
	v_cndmask_b32_e32 v238, v238, v239, vcc
	ds_write_b32 v71, v238
.Lp3_rsQ:
	s_or_b64 exec, exec, s[96:97]
	s_waitcnt lgkmcnt(0)
	s_barrier
	s_waitcnt vmcnt(15)
	ds_write_b128 v121, v[2:5] offset:16
	s_waitcnt vmcnt(14)
	ds_write_b128 v121, v[6:9] offset:36880
	s_waitcnt vmcnt(13)
	ds_write_b128 v121, v[10:13] offset:4624
	s_waitcnt vmcnt(12)
	ds_write_b128 v121, v[14:17] offset:41488
	s_waitcnt vmcnt(11)
	ds_write_b128 v121, v[18:21] offset:9232
	s_waitcnt vmcnt(10)
	ds_write_b128 v121, v[22:25] offset:46096
	s_waitcnt vmcnt(9)
	ds_write_b128 v121, v[26:29] offset:13840
	s_waitcnt vmcnt(8)
	ds_write_b128 v121, v[30:33] offset:50704
	s_waitcnt lgkmcnt(0)
	s_barrier
	global_load_dwordx4 v[148:151], v[80:81], off offset:256
	global_load_dwordx4 v[152:155], v[82:83], off offset:256
	global_load_dwordx4 v[156:159], v[84:85], off offset:256
	global_load_dwordx4 v[160:163], v[86:87], off offset:256
	global_load_dwordx4 v[164:167], v[88:89], off offset:256
	global_load_dwordx4 v[168:171], v[90:91], off offset:256
	global_load_dwordx4 v[172:175], v[92:93], off offset:256
	global_load_dwordx4 v[176:179], v[94:95], off offset:256
	ds_read_b128 v[2:5], v124 offset:16
	ds_read_b128 v[180:183], v124 offset:48
	ds_read_b128 v[18:21], v124 offset:4624
	ds_read_b128 v[184:187], v124 offset:4656
	ds_read_b128 v[6:9], v126 offset:36880
	ds_read_b128 v[190:193], v126 offset:36912
	ds_read_b128 v[22:25], v126 offset:41488
	ds_read_b128 v[194:197], v126 offset:41520
	s_waitcnt lgkmcnt(3)
	v_mfma_f32_32x32x16_bf16 v[34:49], v[6:9], v[2:5], 0
	s_waitcnt lgkmcnt(1)
	v_mfma_f32_32x32x16_bf16 v[50:65], v[22:25], v[2:5], 0
	v_mfma_f32_32x32x16_bf16 v[2:17], v[6:9], v[18:21], 0
	v_mfma_f32_32x32x16_bf16 v[18:33], v[22:25], v[18:21], 0
	ds_read_b128 v[198:201], v124 offset:80
	ds_read_b128 v[202:205], v124 offset:4688
	ds_read_b128 v[206:209], v126 offset:36944
	ds_read_b128 v[210:213], v126 offset:41552
	v_mfma_f32_32x32x16_bf16 v[34:49], v[190:193], v[180:183], v[34:49]
	s_waitcnt lgkmcnt(4)
	v_mfma_f32_32x32x16_bf16 v[50:65], v[194:197], v[180:183], v[50:65]
	v_mfma_f32_32x32x16_bf16 v[2:17], v[190:193], v[184:187], v[2:17]
	v_mfma_f32_32x32x16_bf16 v[18:33], v[194:197], v[184:187], v[18:33]
	ds_read_b128 v[180:183], v124 offset:112
	ds_read_b128 v[184:187], v124 offset:4720
	ds_read_b128 v[190:193], v126 offset:36976
	ds_read_b128 v[194:197], v126 offset:41584
	s_waitcnt lgkmcnt(5)
	v_mfma_f32_32x32x16_bf16 v[34:49], v[206:209], v[198:201], v[34:49]
	s_waitcnt lgkmcnt(4)
	v_mfma_f32_32x32x16_bf16 v[50:65], v[210:213], v[198:201], v[50:65]
	v_mfma_f32_32x32x16_bf16 v[2:17], v[206:209], v[202:205], v[2:17]
	v_mfma_f32_32x32x16_bf16 v[18:33], v[210:213], v[202:205], v[18:33]
	s_waitcnt lgkmcnt(1)
	v_mfma_f32_32x32x16_bf16 v[34:49], v[190:193], v[180:183], v[34:49]
	s_waitcnt lgkmcnt(0)
	v_mfma_f32_32x32x16_bf16 v[50:65], v[194:197], v[180:183], v[50:65]
	v_mfma_f32_32x32x16_bf16 v[2:17], v[190:193], v[184:187], v[2:17]
	v_mfma_f32_32x32x16_bf16 v[18:33], v[194:197], v[184:187], v[18:33]
	s_waitcnt vmcnt(15)
	ds_write_b128 v121, v[96:99] offset:18448
	s_waitcnt vmcnt(14)
	ds_write_b128 v121, v[100:103] offset:55312
	s_waitcnt vmcnt(13)
	ds_write_b128 v121, v[104:107] offset:23056
	s_waitcnt vmcnt(12)
	ds_write_b128 v121, v[108:111] offset:59920
	s_waitcnt vmcnt(11)
	ds_write_b128 v121, v[112:115] offset:27664
	s_waitcnt vmcnt(10)
	ds_write_b128 v121, v[116:119] offset:64528
	s_waitcnt vmcnt(9)
	ds_write_b128 v121, v[140:143] offset:32272
	s_waitcnt vmcnt(8)
	ds_write_b128 v122, v[144:147] offset:32256
	s_waitcnt lgkmcnt(0)
	s_barrier
; template <bool SWAP, class Epi>
; DI void gemm_tile(const u16* __restrict__ A, int lda, const u16* __restrict__ Bt, int ldb, int K, int m0, int n0, char* smem, Epi&& epi) {
;     ...
;   for (int kt = 0; kt < KT; kt += 2) {
;     if (kt + 2 < KT) {
;       const int k0 = (kt + 2) << 6;
; #pragma unroll
;       for (int i = 0; i < 4; ++i) { ra0[i] = *(const u32x4*)(ag + (size_t)i * 32 * lda + k0); rb0[i] = *(const u32x4*)(bg + (size_t)i * 32 * ldb + k0); }
;     }
;     compute(0);
; #pragma unroll
;     for (int i = 0; i < 4; ++i) { *(u32x4*)(asw + 128 * 72 + 32 * i * 72) = ra1[i]; *(u32x4*)(bsw + 128 * 72 + 32 * i * 72) = rb1[i]; }
;     __syncthreads();
;     if (kt + 3 < KT) {
;       const int k0 = (kt + 3) << 6;
; #pragma unroll
;       for (int i = 0; i < 4; ++i) { ra1[i] = *(const u32x4*)(ag + (size_t)i * 32 * lda + k0); rb1[i] = *(const u32x4*)(bg + (size_t)i * 32 * ldb + k0); }
;     }
;     compute(1);
;     if (kt + 2 < KT) {
; #pragma unroll
;       for (int i = 0; i < 4; ++i) { *(u32x4*)(asw + 32 * i * 72) = ra0[i]; *(u32x4*)(bsw + 32 * i * 72) = rb0[i]; }
;     }
;     __syncthreads();
	global_load_dwordx4 v[96:99], v[80:81], off offset:384
	global_load_dwordx4 v[100:103], v[82:83], off offset:384
	global_load_dwordx4 v[104:107], v[84:85], off offset:384
	global_load_dwordx4 v[108:111], v[86:87], off offset:384
	global_load_dwordx4 v[112:115], v[88:89], off offset:384
	global_load_dwordx4 v[116:119], v[90:91], off offset:384
	global_load_dwordx4 v[140:143], v[92:93], off offset:384
	global_load_dwordx4 v[144:147], v[94:95], off offset:384
	ds_read_b128 v[180:183], v124 offset:18448
	ds_read_b128 v[184:187], v124 offset:18480
	ds_read_b128 v[190:193], v124 offset:23056
	ds_read_b128 v[194:197], v124 offset:23088
	ds_read_b128 v[198:201], v126 offset:55312
	ds_read_b128 v[202:205], v126 offset:55344
	ds_read_b128 v[206:209], v126 offset:59920
	ds_read_b128 v[210:213], v126 offset:59952
	s_waitcnt lgkmcnt(3)
	v_mfma_f32_32x32x16_bf16 v[34:49], v[198:201], v[180:183], v[34:49]
	s_waitcnt lgkmcnt(1)
	v_mfma_f32_32x32x16_bf16 v[50:65], v[206:209], v[180:183], v[50:65]
	v_mfma_f32_32x32x16_bf16 v[2:17], v[198:201], v[190:193], v[2:17]
	v_mfma_f32_32x32x16_bf16 v[18:33], v[206:209], v[190:193], v[18:33]
	ds_read_b128 v[180:183], v124 offset:18512
	ds_read_b128 v[190:193], v124 offset:23120
	ds_read_b128 v[198:201], v126 offset:55376
	ds_read_b128 v[206:209], v126 offset:59984
	v_mfma_f32_32x32x16_bf16 v[34:49], v[202:205], v[184:187], v[34:49]
	s_waitcnt lgkmcnt(4)
	v_mfma_f32_32x32x16_bf16 v[50:65], v[210:213], v[184:187], v[50:65]
	v_mfma_f32_32x32x16_bf16 v[2:17], v[202:205], v[194:197], v[2:17]
	v_mfma_f32_32x32x16_bf16 v[18:33], v[210:213], v[194:197], v[18:33]
	ds_read_b128 v[184:187], v124 offset:18544
	ds_read_b128 v[194:197], v124 offset:23152
	ds_read_b128 v[202:205], v126 offset:55408
	ds_read_b128 v[210:213], v126 offset:60016
	s_waitcnt lgkmcnt(5)
	v_mfma_f32_32x32x16_bf16 v[34:49], v[198:201], v[180:183], v[34:49]
	s_waitcnt lgkmcnt(4)
	v_mfma_f32_32x32x16_bf16 v[50:65], v[206:209], v[180:183], v[50:65]
	v_mfma_f32_32x32x16_bf16 v[2:17], v[198:201], v[190:193], v[2:17]
	v_mfma_f32_32x32x16_bf16 v[18:33], v[206:209], v[190:193], v[18:33]
	s_waitcnt lgkmcnt(1)
	v_mfma_f32_32x32x16_bf16 v[34:49], v[202:205], v[184:187], v[34:49]
	s_waitcnt lgkmcnt(0)
	v_mfma_f32_32x32x16_bf16 v[50:65], v[210:213], v[184:187], v[50:65]
	v_mfma_f32_32x32x16_bf16 v[2:17], v[202:205], v[194:197], v[2:17]
	v_mfma_f32_32x32x16_bf16 v[18:33], v[210:213], v[194:197], v[18:33]
	s_waitcnt vmcnt(15)
	ds_write_b128 v121, v[148:151] offset:16
	s_waitcnt vmcnt(14)
	ds_write_b128 v121, v[152:155] offset:36880
	s_waitcnt vmcnt(13)
	ds_write_b128 v121, v[156:159] offset:4624
	s_waitcnt vmcnt(12)
	ds_write_b128 v121, v[160:163] offset:41488
	s_waitcnt vmcnt(11)
	ds_write_b128 v121, v[164:167] offset:9232
	s_waitcnt vmcnt(10)
	ds_write_b128 v121, v[168:171] offset:46096
	s_waitcnt vmcnt(9)
	ds_write_b128 v121, v[172:175] offset:13840
	s_waitcnt vmcnt(8)
	ds_write_b128 v121, v[176:179] offset:50704
	s_waitcnt lgkmcnt(0)
	s_barrier
	global_load_dwordx4 v[148:151], v[80:81], off offset:512
	global_load_dwordx4 v[152:155], v[82:83], off offset:512
	global_load_dwordx4 v[156:159], v[84:85], off offset:512
	global_load_dwordx4 v[160:163], v[86:87], off offset:512
	global_load_dwordx4 v[164:167], v[88:89], off offset:512
	global_load_dwordx4 v[168:171], v[90:91], off offset:512
	global_load_dwordx4 v[172:175], v[92:93], off offset:512
	global_load_dwordx4 v[176:179], v[94:95], off offset:512
	ds_read_b128 v[180:183], v124 offset:16
	ds_read_b128 v[184:187], v124 offset:48
	ds_read_b128 v[190:193], v124 offset:4624
	ds_read_b128 v[194:197], v124 offset:4656
	ds_read_b128 v[198:201], v126 offset:36880
	ds_read_b128 v[202:205], v126 offset:36912
	ds_read_b128 v[206:209], v126 offset:41488
	ds_read_b128 v[210:213], v126 offset:41520
	s_waitcnt lgkmcnt(3)
	v_mfma_f32_32x32x16_bf16 v[34:49], v[198:201], v[180:183], v[34:49]
	s_waitcnt lgkmcnt(1)
	v_mfma_f32_32x32x16_bf16 v[50:65], v[206:209], v[180:183], v[50:65]
	v_mfma_f32_32x32x16_bf16 v[2:17], v[198:201], v[190:193], v[2:17]
	v_mfma_f32_32x32x16_bf16 v[18:33], v[206:209], v[190:193], v[18:33]
	ds_read_b128 v[180:183], v124 offset:80
	ds_read_b128 v[190:193], v124 offset:4688
	ds_read_b128 v[198:201], v126 offset:36944
	ds_read_b128 v[206:209], v126 offset:41552
	v_mfma_f32_32x32x16_bf16 v[34:49], v[202:205], v[184:187], v[34:49]
	s_waitcnt lgkmcnt(4)
	v_mfma_f32_32x32x16_bf16 v[50:65], v[210:213], v[184:187], v[50:65]
	v_mfma_f32_32x32x16_bf16 v[2:17], v[202:205], v[194:197], v[2:17]
	v_mfma_f32_32x32x16_bf16 v[18:33], v[210:213], v[194:197], v[18:33]
	ds_read_b128 v[184:187], v124 offset:112
	ds_read_b128 v[194:197], v124 offset:4720
	ds_read_b128 v[202:205], v126 offset:36976
	ds_read_b128 v[210:213], v126 offset:41584
	s_waitcnt lgkmcnt(5)
	v_mfma_f32_32x32x16_bf16 v[34:49], v[198:201], v[180:183], v[34:49]
	s_waitcnt lgkmcnt(4)
	v_mfma_f32_32x32x16_bf16 v[50:65], v[206:209], v[180:183], v[50:65]
	v_mfma_f32_32x32x16_bf16 v[2:17], v[198:201], v[190:193], v[2:17]
	v_mfma_f32_32x32x16_bf16 v[18:33], v[206:209], v[190:193], v[18:33]
	s_waitcnt lgkmcnt(1)
	v_mfma_f32_32x32x16_bf16 v[34:49], v[202:205], v[184:187], v[34:49]
	s_waitcnt lgkmcnt(0)
	v_mfma_f32_32x32x16_bf16 v[50:65], v[210:213], v[184:187], v[50:65]
	v_mfma_f32_32x32x16_bf16 v[2:17], v[202:205], v[194:197], v[2:17]
	v_mfma_f32_32x32x16_bf16 v[18:33], v[210:213], v[194:197], v[18:33]
	s_waitcnt vmcnt(15)
	ds_write_b128 v121, v[96:99] offset:18448
	s_waitcnt vmcnt(14)
	ds_write_b128 v121, v[100:103] offset:55312
	s_waitcnt vmcnt(13)
	ds_write_b128 v121, v[104:107] offset:23056
	s_waitcnt vmcnt(12)
	ds_write_b128 v121, v[108:111] offset:59920
	s_waitcnt vmcnt(11)
	ds_write_b128 v121, v[112:115] offset:27664
	s_waitcnt vmcnt(10)
	ds_write_b128 v121, v[116:119] offset:64528
	s_waitcnt vmcnt(9)
	ds_write_b128 v121, v[140:143] offset:32272
	s_waitcnt vmcnt(8)
	ds_write_b128 v122, v[144:147] offset:32256
	s_waitcnt lgkmcnt(0)
	s_barrier
; #define MFMA(a, b, c) __builtin_amdgcn_mfma_f32_32x32x16_bf16((a), (b), (c), 0, 0, 0)
; template <bool SWAP, class Epi>
; DI void gemm_tile(const u16* __restrict__ A, int lda, const u16* __restrict__ Bt, int ldb, int K, int m0, int n0, char* smem, Epi&& epi) {
;     ...
;   auto compute = [&](int buf) __attribute__((always_inline)) {
;     bf16x8 af[2][2], bfr[2][2];
;     af[0][0] = *(const bf16x8*)(Asb + buf * 128 * 72);
;     af[0][1] = *(const bf16x8*)(Asb + buf * 128 * 72 + 32 * 72);
;     bfr[0][0] = *(const bf16x8*)(Bsb + buf * 128 * 72);
;     bfr[0][1] = *(const bf16x8*)(Bsb + buf * 128 * 72 + 32 * 72);
; #pragma unroll
;     for (int ks = 0; ks < 4; ++ks) {
;       const int c = ks & 1, n = c ^ 1;
;       if (ks < 3) {
;         af[n][0] = *(const bf16x8*)(Asb + buf * 128 * 72 + (ks + 1) * 16);
;         af[n][1] = *(const bf16x8*)(Asb + buf * 128 * 72 + 32 * 72 + (ks + 1) * 16);
;         bfr[n][0] = *(const bf16x8*)(Bsb + buf * 128 * 72 + (ks + 1) * 16);
;         bfr[n][1] = *(const bf16x8*)(Bsb + buf * 128 * 72 + 32 * 72 + (ks + 1) * 16);
;       }
;       __builtin_amdgcn_sched_barrier(0);
; #pragma unroll
;       for (int mi = 0; mi < 2; ++mi)
; #pragma unroll
;         for (int ni = 0; ni < 2; ++ni) {
;           if (SWAP) acc[mi][ni] = MFMA(bfr[c][ni], af[c][mi], acc[mi][ni]);
;           else acc[mi][ni] = MFMA(af[c][mi], bfr[c][ni], acc[mi][ni]);
;         }
;       __builtin_amdgcn_sched_barrier(0);
;     }
;   };
;   for (int kt = 0; kt < KT; kt += 2) {
;     if (kt + 2 < KT) {
;       const int k0 = (kt + 2) << 6;
; #pragma unroll
;       for (int i = 0; i < 4; ++i) { ra0[i] = *(const u32x4*)(ag + (size_t)i * 32 * lda + k0); rb0[i] = *(const u32x4*)(bg + (size_t)i * 32 * ldb + k0); }
;     }
;     compute(0);
; #pragma unroll
;     for (int i = 0; i < 4; ++i) { *(u32x4*)(asw + 128 * 72 + 32 * i * 72) = ra1[i]; *(u32x4*)(bsw + 128 * 72 + 32 * i * 72) = rb1[i]; }
;     __syncthreads();
;     if (kt + 3 < KT) {
;       const int k0 = (kt + 3) << 6;
; #pragma unroll
;       for (int i = 0; i < 4; ++i) { ra1[i] = *(const u32x4*)(ag + (size_t)i * 32 * lda + k0); rb1[i] = *(const u32x4*)(bg + (size_t)i * 32 * ldb + k0); }
;     }
;     compute(1);
;     if (kt + 2 < KT) {
; #pragma unroll
;       for (int i = 0; i < 4; ++i) { *(u32x4*)(asw + 32 * i * 72) = ra0[i]; *(u32x4*)(bsw + 32 * i * 72) = rb0[i]; }
;     }
;     __syncthreads();
	global_load_dwordx4 v[96:99], v[80:81], off offset:640
	global_load_dwordx4 v[100:103], v[82:83], off offset:640
	global_load_dwordx4 v[104:107], v[84:85], off offset:640
	global_load_dwordx4 v[108:111], v[86:87], off offset:640
	global_load_dwordx4 v[112:115], v[88:89], off offset:640
	global_load_dwordx4 v[116:119], v[90:91], off offset:640
	global_load_dwordx4 v[140:143], v[92:93], off offset:640
	global_load_dwordx4 v[144:147], v[94:95], off offset:640
	ds_read_b128 v[180:183], v124 offset:18448
	ds_read_b128 v[184:187], v124 offset:18480
	ds_read_b128 v[190:193], v124 offset:23056
	ds_read_b128 v[194:197], v124 offset:23088
	ds_read_b128 v[198:201], v126 offset:55312
	ds_read_b128 v[202:205], v126 offset:55344
	ds_read_b128 v[206:209], v126 offset:59920
	ds_read_b128 v[210:213], v126 offset:59952
	s_waitcnt lgkmcnt(3)
	v_mfma_f32_32x32x16_bf16 v[34:49], v[198:201], v[180:183], v[34:49]
	s_waitcnt lgkmcnt(1)
	v_mfma_f32_32x32x16_bf16 v[50:65], v[206:209], v[180:183], v[50:65]
	v_mfma_f32_32x32x16_bf16 v[2:17], v[198:201], v[190:193], v[2:17]
	v_mfma_f32_32x32x16_bf16 v[18:33], v[206:209], v[190:193], v[18:33]
	ds_read_b128 v[180:183], v124 offset:18512
	ds_read_b128 v[190:193], v124 offset:23120
	ds_read_b128 v[198:201], v126 offset:55376
	ds_read_b128 v[206:209], v126 offset:59984
	v_mfma_f32_32x32x16_bf16 v[34:49], v[202:205], v[184:187], v[34:49]
	s_waitcnt lgkmcnt(4)
	v_mfma_f32_32x32x16_bf16 v[50:65], v[210:213], v[184:187], v[50:65]
	v_mfma_f32_32x32x16_bf16 v[2:17], v[202:205], v[194:197], v[2:17]
	v_mfma_f32_32x32x16_bf16 v[18:33], v[210:213], v[194:197], v[18:33]
	ds_read_b128 v[184:187], v124 offset:18544
	ds_read_b128 v[194:197], v124 offset:23152
	ds_read_b128 v[202:205], v126 offset:55408
	ds_read_b128 v[210:213], v126 offset:60016
	s_waitcnt lgkmcnt(5)
	v_mfma_f32_32x32x16_bf16 v[34:49], v[198:201], v[180:183], v[34:49]
	s_waitcnt lgkmcnt(4)
	v_mfma_f32_32x32x16_bf16 v[50:65], v[206:209], v[180:183], v[50:65]
	v_mfma_f32_32x32x16_bf16 v[2:17], v[198:201], v[190:193], v[2:17]
	v_mfma_f32_32x32x16_bf16 v[18:33], v[206:209], v[190:193], v[18:33]
	s_waitcnt lgkmcnt(1)
	v_mfma_f32_32x32x16_bf16 v[34:49], v[202:205], v[184:187], v[34:49]
	s_waitcnt lgkmcnt(0)
	v_mfma_f32_32x32x16_bf16 v[50:65], v[210:213], v[184:187], v[50:65]
	v_mfma_f32_32x32x16_bf16 v[2:17], v[202:205], v[194:197], v[2:17]
	v_mfma_f32_32x32x16_bf16 v[18:33], v[210:213], v[194:197], v[18:33]
	s_waitcnt vmcnt(15)
	ds_write_b128 v121, v[148:151] offset:16
	s_waitcnt vmcnt(14)
	ds_write_b128 v121, v[152:155] offset:36880
	s_waitcnt vmcnt(13)
	ds_write_b128 v121, v[156:159] offset:4624
	s_waitcnt vmcnt(12)
	ds_write_b128 v121, v[160:163] offset:41488
	s_waitcnt vmcnt(11)
	ds_write_b128 v121, v[164:167] offset:9232
	s_waitcnt vmcnt(10)
	ds_write_b128 v121, v[168:171] offset:46096
	s_waitcnt vmcnt(9)
	ds_write_b128 v121, v[172:175] offset:13840
	s_waitcnt vmcnt(8)
	ds_write_b128 v121, v[176:179] offset:50704
	s_waitcnt lgkmcnt(0)
	s_barrier
	global_load_dwordx4 v[148:151], v[80:81], off offset:768
	global_load_dwordx4 v[152:155], v[82:83], off offset:768
	global_load_dwordx4 v[156:159], v[84:85], off offset:768
	global_load_dwordx4 v[160:163], v[86:87], off offset:768
	global_load_dwordx4 v[164:167], v[88:89], off offset:768
	global_load_dwordx4 v[168:171], v[90:91], off offset:768
	global_load_dwordx4 v[172:175], v[92:93], off offset:768
	global_load_dwordx4 v[176:179], v[94:95], off offset:768
	ds_read_b128 v[180:183], v124 offset:16
	ds_read_b128 v[184:187], v124 offset:48
	ds_read_b128 v[190:193], v124 offset:4624
	ds_read_b128 v[194:197], v124 offset:4656
	ds_read_b128 v[198:201], v126 offset:36880
	ds_read_b128 v[202:205], v126 offset:36912
	ds_read_b128 v[206:209], v126 offset:41488
	ds_read_b128 v[210:213], v126 offset:41520
	s_waitcnt lgkmcnt(3)
	v_mfma_f32_32x32x16_bf16 v[34:49], v[198:201], v[180:183], v[34:49]
	s_waitcnt lgkmcnt(1)
	v_mfma_f32_32x32x16_bf16 v[50:65], v[206:209], v[180:183], v[50:65]
	v_mfma_f32_32x32x16_bf16 v[2:17], v[198:201], v[190:193], v[2:17]
	v_mfma_f32_32x32x16_bf16 v[18:33], v[206:209], v[190:193], v[18:33]
	ds_read_b128 v[180:183], v124 offset:80
	ds_read_b128 v[190:193], v124 offset:4688
	ds_read_b128 v[198:201], v126 offset:36944
	ds_read_b128 v[206:209], v126 offset:41552
	v_mfma_f32_32x32x16_bf16 v[34:49], v[202:205], v[184:187], v[34:49]
	s_waitcnt lgkmcnt(4)
	v_mfma_f32_32x32x16_bf16 v[50:65], v[210:213], v[184:187], v[50:65]
	v_mfma_f32_32x32x16_bf16 v[2:17], v[202:205], v[194:197], v[2:17]
	v_mfma_f32_32x32x16_bf16 v[18:33], v[210:213], v[194:197], v[18:33]
	ds_read_b128 v[184:187], v124 offset:112
	ds_read_b128 v[194:197], v124 offset:4720
	ds_read_b128 v[202:205], v126 offset:36976
	ds_read_b128 v[210:213], v126 offset:41584
	s_waitcnt lgkmcnt(5)
	v_mfma_f32_32x32x16_bf16 v[34:49], v[198:201], v[180:183], v[34:49]
	s_waitcnt lgkmcnt(4)
	v_mfma_f32_32x32x16_bf16 v[50:65], v[206:209], v[180:183], v[50:65]
	v_mfma_f32_32x32x16_bf16 v[2:17], v[198:201], v[190:193], v[2:17]
	v_mfma_f32_32x32x16_bf16 v[18:33], v[206:209], v[190:193], v[18:33]
	s_waitcnt lgkmcnt(1)
	v_mfma_f32_32x32x16_bf16 v[34:49], v[202:205], v[184:187], v[34:49]
	s_waitcnt lgkmcnt(0)
	v_mfma_f32_32x32x16_bf16 v[50:65], v[210:213], v[184:187], v[50:65]
	v_mfma_f32_32x32x16_bf16 v[2:17], v[202:205], v[194:197], v[2:17]
	v_mfma_f32_32x32x16_bf16 v[18:33], v[210:213], v[194:197], v[18:33]
	s_waitcnt vmcnt(15)
	ds_write_b128 v121, v[96:99] offset:18448
	s_waitcnt vmcnt(14)
	ds_write_b128 v121, v[100:103] offset:55312
	s_waitcnt vmcnt(13)
	ds_write_b128 v121, v[104:107] offset:23056
	s_waitcnt vmcnt(12)
	ds_write_b128 v121, v[108:111] offset:59920
	s_waitcnt vmcnt(11)
	ds_write_b128 v121, v[112:115] offset:27664
	s_waitcnt vmcnt(10)
	ds_write_b128 v121, v[116:119] offset:64528
	s_waitcnt vmcnt(9)
	ds_write_b128 v121, v[140:143] offset:32272
	s_waitcnt vmcnt(8)
	ds_write_b128 v122, v[144:147] offset:32256
	s_waitcnt lgkmcnt(0)
	s_barrier
; #define MFMA(a, b, c) __builtin_amdgcn_mfma_f32_32x32x16_bf16((a), (b), (c), 0, 0, 0)
; template <bool SWAP, class Epi>
; DI void gemm_tile(const u16* __restrict__ A, int lda, const u16* __restrict__ Bt, int ldb, int K, int m0, int n0, char* smem, Epi&& epi) {
;     ...
;   auto compute = [&](int buf) __attribute__((always_inline)) {
;     bf16x8 af[2][2], bfr[2][2];
;     af[0][0] = *(const bf16x8*)(Asb + buf * 128 * 72);
;     af[0][1] = *(const bf16x8*)(Asb + buf * 128 * 72 + 32 * 72);
;     bfr[0][0] = *(const bf16x8*)(Bsb + buf * 128 * 72);
;     bfr[0][1] = *(const bf16x8*)(Bsb + buf * 128 * 72 + 32 * 72);
; #pragma unroll
;     for (int ks = 0; ks < 4; ++ks) {
;       const int c = ks & 1, n = c ^ 1;
;       if (ks < 3) {
;         af[n][0] = *(const bf16x8*)(Asb + buf * 128 * 72 + (ks + 1) * 16);
;         af[n][1] = *(const bf16x8*)(Asb + buf * 128 * 72 + 32 * 72 + (ks + 1) * 16);
;         bfr[n][0] = *(const bf16x8*)(Bsb + buf * 128 * 72 + (ks + 1) * 16);
;         bfr[n][1] = *(const bf16x8*)(Bsb + buf * 128 * 72 + 32 * 72 + (ks + 1) * 16);
;       }
;       __builtin_amdgcn_sched_barrier(0);
; #pragma unroll
;       for (int mi = 0; mi < 2; ++mi)
; #pragma unroll
;         for (int ni = 0; ni < 2; ++ni) {
;           if (SWAP) acc[mi][ni] = MFMA(bfr[c][ni], af[c][mi], acc[mi][ni]);
;           else acc[mi][ni] = MFMA(af[c][mi], bfr[c][ni], acc[mi][ni]);
;         }
;       __builtin_amdgcn_sched_barrier(0);
;     }
;   };
;   for (int kt = 0; kt < KT; kt += 2) {
;     if (kt + 2 < KT) {
;       const int k0 = (kt + 2) << 6;
; #pragma unroll
;       for (int i = 0; i < 4; ++i) { ra0[i] = *(const u32x4*)(ag + (size_t)i * 32 * lda + k0); rb0[i] = *(const u32x4*)(bg + (size_t)i * 32 * ldb + k0); }
;     }
;     compute(0);
; #pragma unroll
;     for (int i = 0; i < 4; ++i) { *(u32x4*)(asw + 128 * 72 + 32 * i * 72) = ra1[i]; *(u32x4*)(bsw + 128 * 72 + 32 * i * 72) = rb1[i]; }
;     __syncthreads();
;     if (kt + 3 < KT) {
;       const int k0 = (kt + 3) << 6;
; #pragma unroll
;       for (int i = 0; i < 4; ++i) { ra1[i] = *(const u32x4*)(ag + (size_t)i * 32 * lda + k0); rb1[i] = *(const u32x4*)(bg + (size_t)i * 32 * ldb + k0); }
;     }
;     compute(1);
;     if (kt + 2 < KT) {
; #pragma unroll
;       for (int i = 0; i < 4; ++i) { *(u32x4*)(asw + 32 * i * 72) = ra0[i]; *(u32x4*)(bsw + 32 * i * 72) = rb0[i]; }
;     }
;     __syncthreads();
	global_load_dwordx4 v[96:99], v[80:81], off offset:896
	s_nop 0
	global_load_dwordx4 v[80:83], v[82:83], off offset:896
	s_nop 0
	global_load_dwordx4 v[100:103], v[84:85], off offset:896
	s_nop 0
	global_load_dwordx4 v[84:87], v[86:87], off offset:896
	s_nop 0
	global_load_dwordx4 v[104:107], v[88:89], off offset:896
	s_nop 0
	global_load_dwordx4 v[88:91], v[90:91], off offset:896
	s_nop 0
	global_load_dwordx4 v[108:111], v[92:93], off offset:896
	s_nop 0
	global_load_dwordx4 v[92:95], v[94:95], off offset:896
	ds_read_b128 v[112:115], v124 offset:18448
	ds_read_b128 v[116:119], v124 offset:18480
	ds_read_b128 v[140:143], v124 offset:23056
	ds_read_b128 v[144:147], v124 offset:23088
	ds_read_b128 v[180:183], v126 offset:55312
	ds_read_b128 v[184:187], v126 offset:55344
	ds_read_b128 v[190:193], v126 offset:59920
	ds_read_b128 v[194:197], v126 offset:59952
	s_waitcnt lgkmcnt(3)
	v_mfma_f32_32x32x16_bf16 v[34:49], v[180:183], v[112:115], v[34:49]
	s_waitcnt lgkmcnt(1)
	v_mfma_f32_32x32x16_bf16 v[50:65], v[190:193], v[112:115], v[50:65]
	v_mfma_f32_32x32x16_bf16 v[2:17], v[180:183], v[140:143], v[2:17]
	v_mfma_f32_32x32x16_bf16 v[18:33], v[190:193], v[140:143], v[18:33]
	ds_read_b128 v[112:115], v124 offset:18512
	ds_read_b128 v[140:143], v124 offset:23120
	ds_read_b128 v[180:183], v126 offset:55376
	ds_read_b128 v[190:193], v126 offset:59984
	v_mfma_f32_32x32x16_bf16 v[34:49], v[184:187], v[116:119], v[34:49]
	s_waitcnt lgkmcnt(4)
	v_mfma_f32_32x32x16_bf16 v[50:65], v[194:197], v[116:119], v[50:65]
	v_mfma_f32_32x32x16_bf16 v[2:17], v[184:187], v[144:147], v[2:17]
	v_mfma_f32_32x32x16_bf16 v[18:33], v[194:197], v[144:147], v[18:33]
	ds_read_b128 v[116:119], v124 offset:18544
	ds_read_b128 v[144:147], v124 offset:23152
	ds_read_b128 v[184:187], v126 offset:55408
	ds_read_b128 v[194:197], v126 offset:60016
	s_waitcnt lgkmcnt(5)
	v_mfma_f32_32x32x16_bf16 v[34:49], v[180:183], v[112:115], v[34:49]
	s_waitcnt lgkmcnt(4)
	v_mfma_f32_32x32x16_bf16 v[50:65], v[190:193], v[112:115], v[50:65]
	v_mfma_f32_32x32x16_bf16 v[2:17], v[180:183], v[140:143], v[2:17]
	v_mfma_f32_32x32x16_bf16 v[18:33], v[190:193], v[140:143], v[18:33]
	s_waitcnt lgkmcnt(1)
	v_mfma_f32_32x32x16_bf16 v[34:49], v[184:187], v[116:119], v[34:49]
	s_waitcnt lgkmcnt(0)
	v_mfma_f32_32x32x16_bf16 v[50:65], v[194:197], v[116:119], v[50:65]
	v_mfma_f32_32x32x16_bf16 v[2:17], v[184:187], v[144:147], v[2:17]
	v_mfma_f32_32x32x16_bf16 v[18:33], v[194:197], v[144:147], v[18:33]
	s_waitcnt vmcnt(15)
	ds_write_b128 v121, v[148:151] offset:16
	s_waitcnt vmcnt(14)
	ds_write_b128 v121, v[152:155] offset:36880
	s_waitcnt vmcnt(13)
	ds_write_b128 v121, v[156:159] offset:4624
	s_waitcnt vmcnt(12)
	ds_write_b128 v121, v[160:163] offset:41488
	s_waitcnt vmcnt(11)
	ds_write_b128 v121, v[164:167] offset:9232
	s_waitcnt vmcnt(10)
	ds_write_b128 v121, v[168:171] offset:46096
	s_waitcnt vmcnt(9)
	ds_write_b128 v121, v[172:175] offset:13840
	s_waitcnt vmcnt(8)
	ds_write_b128 v121, v[176:179] offset:50704
	s_waitcnt lgkmcnt(0)
	s_barrier
	ds_read_b128 v[112:115], v124 offset:16
	ds_read_b128 v[116:119], v124 offset:48
	ds_read_b128 v[140:143], v124 offset:4624
	ds_read_b128 v[144:147], v124 offset:4656
	ds_read_b128 v[148:151], v126 offset:36880
	ds_read_b128 v[152:155], v126 offset:36912
	ds_read_b128 v[156:159], v126 offset:41488
	ds_read_b128 v[160:163], v126 offset:41520
	s_waitcnt lgkmcnt(3)
	v_mfma_f32_32x32x16_bf16 v[34:49], v[148:151], v[112:115], v[34:49]
	s_waitcnt lgkmcnt(1)
	v_mfma_f32_32x32x16_bf16 v[50:65], v[156:159], v[112:115], v[50:65]
	v_mfma_f32_32x32x16_bf16 v[2:17], v[148:151], v[140:143], v[2:17]
	v_mfma_f32_32x32x16_bf16 v[18:33], v[156:159], v[140:143], v[18:33]
	ds_read_b128 v[112:115], v124 offset:80
	ds_read_b128 v[140:143], v124 offset:4688
	ds_read_b128 v[148:151], v126 offset:36944
	ds_read_b128 v[156:159], v126 offset:41552
	v_mfma_f32_32x32x16_bf16 v[34:49], v[152:155], v[116:119], v[34:49]
	s_waitcnt lgkmcnt(4)
	v_mfma_f32_32x32x16_bf16 v[50:65], v[160:163], v[116:119], v[50:65]
	v_mfma_f32_32x32x16_bf16 v[2:17], v[152:155], v[144:147], v[2:17]
	v_mfma_f32_32x32x16_bf16 v[18:33], v[160:163], v[144:147], v[18:33]
	ds_read_b128 v[116:119], v124 offset:112
	ds_read_b128 v[144:147], v124 offset:4720
	ds_read_b128 v[152:155], v126 offset:36976
	ds_read_b128 v[160:163], v126 offset:41584
	s_waitcnt lgkmcnt(5)
	v_mfma_f32_32x32x16_bf16 v[34:49], v[148:151], v[112:115], v[34:49]
	s_waitcnt lgkmcnt(4)
	v_mfma_f32_32x32x16_bf16 v[50:65], v[156:159], v[112:115], v[50:65]
	v_mfma_f32_32x32x16_bf16 v[2:17], v[148:151], v[140:143], v[2:17]
	v_mfma_f32_32x32x16_bf16 v[18:33], v[156:159], v[140:143], v[18:33]
	s_waitcnt lgkmcnt(1)
	v_mfma_f32_32x32x16_bf16 v[34:49], v[152:155], v[116:119], v[34:49]
	s_waitcnt lgkmcnt(0)
	v_mfma_f32_32x32x16_bf16 v[50:65], v[160:163], v[116:119], v[50:65]
	v_mfma_f32_32x32x16_bf16 v[2:17], v[152:155], v[144:147], v[2:17]
	v_mfma_f32_32x32x16_bf16 v[18:33], v[160:163], v[144:147], v[18:33]
	s_waitcnt vmcnt(7)
	ds_write_b128 v121, v[96:99] offset:18448
	s_waitcnt vmcnt(6)
	ds_write_b128 v121, v[80:83] offset:55312
	s_waitcnt vmcnt(5)
	ds_write_b128 v121, v[100:103] offset:23056
	s_waitcnt vmcnt(4)
	ds_write_b128 v121, v[84:87] offset:59920
	s_waitcnt vmcnt(3)
	ds_write_b128 v121, v[104:107] offset:27664
	s_waitcnt vmcnt(2)
	ds_write_b128 v121, v[88:91] offset:64528
	s_waitcnt vmcnt(1)
	ds_write_b128 v121, v[108:111] offset:32272
	s_waitcnt vmcnt(0)
	ds_write_b128 v122, v[92:95] offset:32256
	s_waitcnt lgkmcnt(0)
	s_barrier
; template <bool SWAP, class Epi>
; DI void gemm_tile(const u16* __restrict__ A, int lda, const u16* __restrict__ Bt, int ldb, int K, int m0, int n0, char* smem, Epi&& epi) {
;     ...
;   auto compute = [&](int buf) __attribute__((always_inline)) {
;     bf16x8 af[2][2], bfr[2][2];
;     af[0][0] = *(const bf16x8*)(Asb + buf * 128 * 72);
;     af[0][1] = *(const bf16x8*)(Asb + buf * 128 * 72 + 32 * 72);
;     bfr[0][0] = *(const bf16x8*)(Bsb + buf * 128 * 72);
;     bfr[0][1] = *(const bf16x8*)(Bsb + buf * 128 * 72 + 32 * 72);
; #pragma unroll
;     for (int ks = 0; ks < 4; ++ks) {
;       const int c = ks & 1, n = c ^ 1;
;       if (ks < 3) {
;         af[n][0] = *(const bf16x8*)(Asb + buf * 128 * 72 + (ks + 1) * 16);
;         af[n][1] = *(const bf16x8*)(Asb + buf * 128 * 72 + 32 * 72 + (ks + 1) * 16);
;         bfr[n][0] = *(const bf16x8*)(Bsb + buf * 128 * 72 + (ks + 1) * 16);
;         bfr[n][1] = *(const bf16x8*)(Bsb + buf * 128 * 72 + 32 * 72 + (ks + 1) * 16);
;       }
;       __builtin_amdgcn_sched_barrier(0);
; #pragma unroll
;       for (int mi = 0; mi < 2; ++mi)
; #pragma unroll
;         for (int ni = 0; ni < 2; ++ni) {
;           if (SWAP) acc[mi][ni] = MFMA(bfr[c][ni], af[c][mi], acc[mi][ni]);
;           else acc[mi][ni] = MFMA(af[c][mi], bfr[c][ni], acc[mi][ni]);
;         }
;       __builtin_amdgcn_sched_barrier(0);
;     }
;   };
; DI void phase3(const Params& p, char* smem) {
;     ...
;       gemm_tile<true>(P + 3072, INC, (const u16*)(p.ws + WS_WUQT), 512, 512, tm * 128, tn * 128, smem, [&](f32x16 (&acc)[2][2], int mb, int nb, int r, int hi) __attribute__((always_inline)) {
;         const bool is_rope = ((nb >> 6) % 3) == 2;
; #pragma unroll
;         for (int mi = 0; mi < 2; ++mi) {
;           const int row = mb + mi * 32 + r;
;           const float sc = rs[row - tm * 128] * qscale;
;           const int pos = row & (S_ - 1);
; #pragma unroll
;           for (int g = 0; g < 4; ++g) {
;             const int j = hi * 4 + 8 * g;
;             float a0[4], a1[4];
; #pragma unroll
;             for (int e = 0; e < 4; ++e) { a0[e] = acc[mi][0][4 * g + e] * sc; a1[e] = acc[mi][1][4 * g + e] * sc; }
;             if (is_rope) {
; #pragma unroll
;               for (int e = 0; e < 4; ++e) {
;                 const float2 cs = rope[pos * 32 + j + e];
;                 const float x1 = a0[e], x2 = a1[e];
	ds_read_b128 v[80:83], v124 offset:18448
	ds_read_b128 v[84:87], v124 offset:18480
	ds_read_b128 v[88:91], v124 offset:23056
	ds_read_b128 v[92:95], v124 offset:23088
	ds_read_b128 v[96:99], v126 offset:55312
	ds_read_b128 v[100:103], v126 offset:55344
	ds_read_b128 v[104:107], v126 offset:59920
	ds_read_b128 v[108:111], v126 offset:59952
	s_waitcnt lgkmcnt(3)
	v_mfma_f32_32x32x16_bf16 v[34:49], v[96:99], v[80:83], v[34:49]
	s_waitcnt lgkmcnt(1)
	v_mfma_f32_32x32x16_bf16 v[50:65], v[104:107], v[80:83], v[50:65]
	v_mfma_f32_32x32x16_bf16 v[2:17], v[96:99], v[88:91], v[2:17]
	v_mfma_f32_32x32x16_bf16 v[18:33], v[104:107], v[88:91], v[18:33]
	ds_read_b128 v[80:83], v124 offset:18512
	ds_read_b128 v[88:91], v124 offset:23120
	ds_read_b128 v[96:99], v126 offset:55376
	ds_read_b128 v[104:107], v126 offset:59984
	v_mfma_f32_32x32x16_bf16 v[34:49], v[100:103], v[84:87], v[34:49]
	s_waitcnt lgkmcnt(4)
	v_mfma_f32_32x32x16_bf16 v[50:65], v[108:111], v[84:87], v[50:65]
	v_mfma_f32_32x32x16_bf16 v[2:17], v[100:103], v[92:95], v[2:17]
	v_mfma_f32_32x32x16_bf16 v[18:33], v[108:111], v[92:95], v[18:33]
	ds_read_b128 v[84:87], v124 offset:18544
	ds_read_b128 v[92:95], v124 offset:23152
	ds_read_b128 v[100:103], v126 offset:55408
	ds_read_b128 v[108:111], v126 offset:60016
	s_waitcnt lgkmcnt(5)
	v_mfma_f32_32x32x16_bf16 v[34:49], v[96:99], v[80:83], v[34:49]
	s_waitcnt lgkmcnt(4)
	v_mfma_f32_32x32x16_bf16 v[50:65], v[104:107], v[80:83], v[50:65]
	v_mfma_f32_32x32x16_bf16 v[2:17], v[96:99], v[88:91], v[2:17]
	v_mfma_f32_32x32x16_bf16 v[18:33], v[104:107], v[88:91], v[18:33]
	s_waitcnt lgkmcnt(1)
	v_mfma_f32_32x32x16_bf16 v[34:49], v[100:103], v[84:87], v[34:49]
	s_waitcnt lgkmcnt(0)
	v_mfma_f32_32x32x16_bf16 v[50:65], v[108:111], v[84:87], v[50:65]
	v_mfma_f32_32x32x16_bf16 v[2:17], v[100:103], v[92:95], v[2:17]
	v_mfma_f32_32x32x16_bf16 v[18:33], v[108:111], v[92:95], v[18:33]
	v_or_b32_e32 v80, s50, v129
	s_barrier
	v_ashrrev_i32_e32 v66, 6, v80
	ds_read_b32 v82, v130
	v_mul_hi_i32 v79, v66, s91
	v_lshrrev_b32_e32 v81, 31, v79
	v_add_u32_e32 v79, v79, v81
	v_lshl_add_u32 v79, v79, 1, v79
	s_lshl_b32 s50, s16, 18
	v_sub_u32_e32 v66, v66, v79
	s_waitcnt lgkmcnt(0)
	v_mul_f32_e32 v82, 0x3dd53b94, v82
	v_subrev_u32_e32 v79, s50, v136
	v_cmp_eq_u32_e32 vcc, 2, v66
	v_add_u32_e32 v66, 0xfffc0000, v79
	v_mov_b32_e32 v84, v34
	v_mov_b32_e32 v85, v51
	v_mov_b32_e32 v51, v35
	v_mul_f32_e32 v34, v36, v82
	v_mov_b32_e32 v36, v53
	v_and_b32_e32 v87, 0xfbe0, v66
	v_pk_mul_f32 v[84:85], v[84:85], v[82:83] op_sel_hi:[1,0]
	v_pk_mul_f32 v[50:51], v[50:51], v[82:83] op_sel_hi:[1,0]
	v_mul_f32_e32 v52, v52, v82
	v_pk_mul_f32 v[36:37], v[36:37], v[82:83] op_sel_hi:[1,0]
	s_and_saveexec_b64 s[50:51], vcc
	s_cbranch_execz .LBB0_521
	v_or_b32_e32 v35, v87, v70
	v_lshlrev_b32_e32 v35, 3, v35
	global_load_dwordx4 v[88:91], v35, s[6:7]
	global_load_dwordx4 v[92:95], v35, s[6:7] offset:16
	v_mov_b32_e32 v96, v50
	v_mov_b32_e32 v97, v85
	s_waitcnt vmcnt(1)
	v_mov_b32_e32 v98, v89
	v_mov_b32_e32 v99, v90
	v_mov_b32_e32 v100, v88
	v_mov_b32_e32 v101, v91
	v_mov_b32_e32 v102, v89
	v_mov_b32_e32 v103, v91
	v_mov_b32_e32 v89, v90
	s_waitcnt vmcnt(0)
	v_mul_f32_e32 v90, v34, v92
	v_mul_f32_e32 v104, v52, v93
	v_mul_f32_e32 v52, v52, v92
	v_mul_f32_e32 v92, v34, v93
	v_pk_mul_f32 v[34:35], v[36:37], v[94:95] op_sel:[1,0] op_sel_hi:[0,1]
	v_pk_mul_f32 v[36:37], v[36:37], v[94:95]
	v_pk_mul_f32 v[94:95], v[50:51], v[100:101]
	v_pk_mul_f32 v[96:97], v[96:97], v[102:103]
	v_mov_b32_e32 v50, v84
	v_mov_b32_e32 v91, v34
	v_mov_b32_e32 v105, v35
	v_mov_b32_e32 v53, v36
	v_mov_b32_e32 v93, v37
	v_pk_fma_f32 v[88:89], v[50:51], v[88:89], v[96:97] neg_lo:[0,0,1] neg_hi:[0,0,1]
	v_pk_add_f32 v[34:35], v[90:91], v[104:105] neg_lo:[0,1] neg_hi:[0,1]
	v_pk_fma_f32 v[50:51], v[84:85], v[98:99], v[94:95]
	v_pk_add_f32 v[52:53], v[52:53], v[92:93]
	v_mov_b32_e32 v85, v51
	v_mov_b32_e32 v36, v53
	v_mov_b32_e32 v84, v88
	v_mov_b32_e32 v51, v89
	v_mov_b32_e32 v37, v35
